# K-loop: opening barrier of each compute segment joined after the segment's first 2 MFMAs
# speedup vs baseline: 1.0017x; 1.0017x over previous
; #define PG8_STAGE(bufoff, gbase, voff) do { _Pragma("unroll") for (int _i = 0; _i < 2; ++_i) \
;         __builtin_amdgcn_global_load_lds((const unsigned*)((const char*)(gbase) + (voff)[_i]), (LAS unsigned*)(lds + (bufoff) + ldsw + _i * 8192), 16, 0, 0); } while (0)
; #define PG8_LDA(dst, b, h) do { _Pragma("unroll") for (int m = 0; m < 4; ++m) _Pragma("unroll") for (int k = 0; k < 2; ++k) dst[m][k] = *(const LAS bf16x8*)(lds + PG8_SA(b, h) + aoff + m * 2048 + k * 1024); } while (0)
; #define PG8_LDB(dst, b, h) do { _Pragma("unroll") for (int n = 0; n < 2; ++n) _Pragma("unroll") for (int k = 0; k < 2; ++k) dst[n][k] = *(const LAS bf16x8*)(lds + PG8_SB(b, h) + boff + n * 2048 + k * 1024); } while (0)
; #define PG8_WAIT_V(n) asm volatile("s_waitcnt vmcnt(" #n ")" ::: "memory")
; template <class Epi, int AMODE>
; __device__ __forceinline__ void gemm_phase(LAS unsigned char* lds, const Gemm g, const StaticOrder& S, const Epi& E, int stagger_us, int tid_in) {
;     ...
;         for (int t = 0; t < nt; t += 2) {
;             const bool last = (t == nt - 2);
;             const char* a1 = cA + (size_t)(t + 1) * kstep;
;             const char* a2 = last ? nA : cA + (size_t)(t + 2) * kstep; const char* b2 = last ? nB : cB + (size_t)(t + 2) * kstep;
;             const char* a3 = a2 + kstep; const char* b3 = b2 + kstep;
;             PG8_LDB(B0, 0, 0); PG8_LDB(B1, 0, 1); PG8_SCHED; PG8_LDA(At, 0, 0); PG8_STAGE(PG8_SA(1, 1), a1 + hstepA, voffA);
;             PG8_WAIT_V(8); PG8_WAIT_L(0); PG8_BAR; PG8_MMA(0, 0, At, B0); PG8_MMA(0, 1, At, B1); PG8_BAR; PG8_SCHED;
;             PG8_LDA(At, 0, 1); PG8_STAGE(PG8_SB(0, 0), b2, voffB); PG8_STAGE(PG8_SB(0, 1), b2 + hstepB, voffB); PG8_STAGE(PG8_SA(0, 0), a2, voffA);
;             PG8_WAIT_V(8); PG8_WAIT_L(0); PG8_BAR; PG8_MMA(1, 0, At, B0); PG8_MMA(1, 1, At, B1); PG8_BAR; PG8_SCHED;
;             PG8_LDB(B0, 1, 0); PG8_LDB(B1, 1, 1); PG8_SCHED; PG8_LDA(At, 1, 0); PG8_STAGE(PG8_SA(0, 1), a2 + hstepA, voffA);
;             PG8_WAIT_V(8); PG8_WAIT_L(0); PG8_BAR; PG8_MMA(0, 0, At, B0); PG8_MMA(0, 1, At, B1); PG8_BAR; PG8_SCHED;
;             PG8_LDA(At, 1, 1); PG8_STAGE(PG8_SB(1, 0), b3, voffB); PG8_STAGE(PG8_SB(1, 1), b3 + hstepB, voffB); PG8_STAGE(PG8_SA(1, 0), a3, voffA);
;             PG8_WAIT_V(8); PG8_WAIT_L(0); PG8_BAR; PG8_MMA(1, 0, At, B0); PG8_MMA(1, 1, At, B1); PG8_BAR; PG8_SCHED;
.LBB0_396:
	s_add_u32 s4, s60, 0xfff80080
	s_addc_u32 s5, s61, -1
	s_add_i32 s30, 0, 0x10000
	s_cmp_eq_u32 s29, 28
	s_cselect_b32 s7, s27, s5
	s_cselect_b32 s6, s28, s4
	v_add_u32_e32 v140, s30, v162
	s_cselect_b32 s5, s49, vcc_hi
	s_cselect_b32 s4, s51, vcc_lo
	s_add_i32 s44, 0, 0x14000
	ds_read_b128 v[144:147], v140
	ds_read_b128 v[148:151], v140 offset:1024
	ds_read_b128 v[152:155], v140 offset:2048
	ds_read_b128 v[156:159], v140 offset:3072
	v_add_u32_e32 v140, s44, v162
	ds_read_b128 v[166:169], v140
	ds_read_b128 v[170:173], v140 offset:1024
	ds_read_b128 v[174:177], v140 offset:2048
	ds_read_b128 v[178:181], v140 offset:3072
	v_lshl_add_u64 v[140:141], s[60:61], 0, v[136:137]
	s_add_i32 m0, s57, 0xc000
	ds_read_b128 v[182:185], v164
	ds_read_b128 v[186:189], v164 offset:1024
	ds_read_b128 v[190:193], v164 offset:2048
	ds_read_b128 v[194:197], v164 offset:3072
	ds_read_b128 v[198:201], v164 offset:4096
	ds_read_b128 v[202:205], v164 offset:5120
	ds_read_b128 v[206:209], v164 offset:6144
	ds_read_b128 v[210:213], v164 offset:7168
	global_load_lds_dwordx4 v[140:141], off
	s_add_i32 m0, s57, 0xe000
	v_lshl_add_u64 v[140:141], s[60:61], 0, v[138:139]
	global_load_lds_dwordx4 v[140:141], off
	s_setprio 1
	s_waitcnt vmcnt(8) lgkmcnt(0)
	v_mfma_f32_16x16x32_bf16 v[126:129], v[144:147], v[182:185], v[126:129]
	v_mfma_f32_16x16x32_bf16 v[122:125], v[152:155], v[182:185], v[122:125]
	s_barrier
	v_mfma_f32_16x16x32_bf16 v[110:113], v[144:147], v[190:193], v[110:113]
	v_mfma_f32_16x16x32_bf16 v[106:109], v[152:155], v[190:193], v[106:109]
	v_mfma_f32_16x16x32_bf16 v[94:97], v[144:147], v[198:201], v[94:97]
	v_mfma_f32_16x16x32_bf16 v[90:93], v[152:155], v[198:201], v[90:93]
	v_mfma_f32_16x16x32_bf16 v[78:81], v[144:147], v[206:209], v[78:81]
	v_mfma_f32_16x16x32_bf16 v[74:77], v[152:155], v[206:209], v[74:77]
	v_mfma_f32_16x16x32_bf16 v[126:129], v[148:151], v[186:189], v[126:129]
	v_mfma_f32_16x16x32_bf16 v[122:125], v[156:159], v[186:189], v[122:125]
	v_mfma_f32_16x16x32_bf16 v[110:113], v[148:151], v[194:197], v[110:113]
	v_mfma_f32_16x16x32_bf16 v[106:109], v[156:159], v[194:197], v[106:109]
	v_mfma_f32_16x16x32_bf16 v[94:97], v[148:151], v[202:205], v[94:97]
	v_mfma_f32_16x16x32_bf16 v[90:93], v[156:159], v[202:205], v[90:93]
	v_mfma_f32_16x16x32_bf16 v[78:81], v[148:151], v[210:213], v[78:81]
	v_mfma_f32_16x16x32_bf16 v[74:77], v[156:159], v[210:213], v[74:77]
	v_mfma_f32_16x16x32_bf16 v[118:121], v[166:169], v[182:185], v[118:121]
	v_mfma_f32_16x16x32_bf16 v[114:117], v[174:177], v[182:185], v[114:117]
	v_mfma_f32_16x16x32_bf16 v[102:105], v[166:169], v[190:193], v[102:105]
	v_mfma_f32_16x16x32_bf16 v[98:101], v[174:177], v[190:193], v[98:101]
	v_mfma_f32_16x16x32_bf16 v[86:89], v[166:169], v[198:201], v[86:89]
	v_mfma_f32_16x16x32_bf16 v[82:85], v[174:177], v[198:201], v[82:85]
	v_mfma_f32_16x16x32_bf16 v[70:73], v[166:169], v[206:209], v[70:73]
	v_mfma_f32_16x16x32_bf16 v[66:69], v[174:177], v[206:209], v[66:69]
	v_mfma_f32_16x16x32_bf16 v[118:121], v[170:173], v[186:189], v[118:121]
	v_mfma_f32_16x16x32_bf16 v[114:117], v[178:181], v[186:189], v[114:117]
	v_mfma_f32_16x16x32_bf16 v[102:105], v[170:173], v[194:197], v[102:105]
	v_mfma_f32_16x16x32_bf16 v[98:101], v[178:181], v[194:197], v[98:101]
	v_mfma_f32_16x16x32_bf16 v[86:89], v[170:173], v[202:205], v[86:89]
	v_mfma_f32_16x16x32_bf16 v[82:85], v[178:181], v[202:205], v[82:85]
	v_mfma_f32_16x16x32_bf16 v[70:73], v[170:173], v[210:213], v[70:73]
	v_mfma_f32_16x16x32_bf16 v[66:69], v[178:181], v[210:213], v[66:69]
	s_setprio 0
	s_barrier
	s_add_i32 s30, s30, s66
	v_lshl_add_u64 v[140:141], s[4:5], 0, v[0:1]
	s_mov_b32 m0, s30
	ds_read_b128 v[182:185], v164 offset:16384
	ds_read_b128 v[186:189], v164 offset:17408
	ds_read_b128 v[190:193], v164 offset:18432
	ds_read_b128 v[194:197], v164 offset:19456
	ds_read_b128 v[198:201], v164 offset:20480
	ds_read_b128 v[202:205], v164 offset:21504
	ds_read_b128 v[206:209], v164 offset:22528
	ds_read_b128 v[210:213], v164 offset:23552
	global_load_lds_dwordx4 v[140:141], off
	s_add_i32 m0, s30, 0x2000
	s_add_u32 s30, s4, 0x80000
	v_lshl_add_u64 v[160:161], s[4:5], 0, v[130:131]
	s_addc_u32 s31, s5, 0
	s_add_i32 s44, s44, s66
	global_load_lds_dwordx4 v[160:161], off
	v_lshl_add_u64 v[214:215], s[30:31], 0, v[0:1]
	s_mov_b32 m0, s44
	v_lshl_add_u64 v[216:217], s[6:7], 0, v[132:133]
	global_load_lds_dwordx4 v[214:215], off
	s_add_i32 m0, s44, 0x2000
	v_lshl_add_u64 v[214:215], s[30:31], 0, v[130:131]
	global_load_lds_dwordx4 v[214:215], off
	s_mov_b32 m0, s57
	v_lshl_add_u64 v[214:215], s[6:7], 0, v[134:135]
	global_load_lds_dwordx4 v[214:215], off
	s_mov_b32 m0, s59
	s_nop 0
	global_load_lds_dwordx4 v[216:217], off
	s_setprio 1
	s_waitcnt vmcnt(8) lgkmcnt(0)
	v_mfma_f32_16x16x32_bf16 v[62:65], v[144:147], v[182:185], v[62:65]
	v_mfma_f32_16x16x32_bf16 v[58:61], v[152:155], v[182:185], v[58:61]
	s_barrier
; #define PG8_STAGE(bufoff, gbase, voff) do { _Pragma("unroll") for (int _i = 0; _i < 2; ++_i) \
;         __builtin_amdgcn_global_load_lds((const unsigned*)((const char*)(gbase) + (voff)[_i]), (LAS unsigned*)(lds + (bufoff) + ldsw + _i * 8192), 16, 0, 0); } while (0)
; #define PG8_LDA(dst, b, h) do { _Pragma("unroll") for (int m = 0; m < 4; ++m) _Pragma("unroll") for (int k = 0; k < 2; ++k) dst[m][k] = *(const LAS bf16x8*)(lds + PG8_SA(b, h) + aoff + m * 2048 + k * 1024); } while (0)
; #define PG8_LDB(dst, b, h) do { _Pragma("unroll") for (int n = 0; n < 2; ++n) _Pragma("unroll") for (int k = 0; k < 2; ++k) dst[n][k] = *(const LAS bf16x8*)(lds + PG8_SB(b, h) + boff + n * 2048 + k * 1024); } while (0)
; #define PG8_MMA(ai, bj, At, Bt) do { __builtin_amdgcn_s_setprio(1); _Pragma("unroll") for (int m = 0; m < 4; ++m) _Pragma("unroll") for (int n = 0; n < 2; ++n) _Pragma("unroll") for (int k = 0; k < 2; ++k) \
;         acc[ai][bj][m][n] = __builtin_amdgcn_mfma_f32_16x16x32_bf16(Bt[n][k], At[m][k], acc[ai][bj][m][n], 0, 0, 0); __builtin_amdgcn_s_setprio(0); } while (0)
; #define PG8_WAIT_V(n) asm volatile("s_waitcnt vmcnt(" #n ")" ::: "memory")
; #define PG8_WAIT_L(n) asm volatile("s_waitcnt lgkmcnt(" #n ")" ::: "memory")
; #define PG8_BAR __builtin_amdgcn_s_barrier()
; #define PG8_SCHED __builtin_amdgcn_sched_barrier(0)
; template <class Epi, int AMODE>
; __device__ __forceinline__ void gemm_phase(LAS unsigned char* lds, const Gemm g, const StaticOrder& S, const Epi& E, int stagger_us, int tid_in) {
;     ...
;             PG8_WAIT_V(8); PG8_WAIT_L(0); PG8_BAR; PG8_MMA(1, 0, At, B0); PG8_MMA(1, 1, At, B1); PG8_BAR; PG8_SCHED;
;             PG8_LDB(B0, 1, 0); PG8_LDB(B1, 1, 1); PG8_SCHED; PG8_LDA(At, 1, 0); PG8_STAGE(PG8_SA(0, 1), a2 + hstepA, voffA);
;             PG8_WAIT_V(8); PG8_WAIT_L(0); PG8_BAR; PG8_MMA(0, 0, At, B0); PG8_MMA(0, 1, At, B1); PG8_BAR; PG8_SCHED;
;             PG8_LDA(At, 1, 1); PG8_STAGE(PG8_SB(1, 0), b3, voffB); PG8_STAGE(PG8_SB(1, 1), b3 + hstepB, voffB); PG8_STAGE(PG8_SA(1, 0), a3, voffA);
	v_mfma_f32_16x16x32_bf16 v[46:49], v[144:147], v[190:193], v[46:49]
	v_mfma_f32_16x16x32_bf16 v[42:45], v[152:155], v[190:193], v[42:45]
	v_mfma_f32_16x16x32_bf16 v[30:33], v[144:147], v[198:201], v[30:33]
	v_mfma_f32_16x16x32_bf16 v[26:29], v[152:155], v[198:201], v[26:29]
	v_mfma_f32_16x16x32_bf16 v[14:17], v[144:147], v[206:209], v[14:17]
	v_mfma_f32_16x16x32_bf16 v[10:13], v[152:155], v[206:209], v[10:13]
	v_mfma_f32_16x16x32_bf16 v[62:65], v[148:151], v[186:189], v[62:65]
	v_mfma_f32_16x16x32_bf16 v[58:61], v[156:159], v[186:189], v[58:61]
	v_mfma_f32_16x16x32_bf16 v[46:49], v[148:151], v[194:197], v[46:49]
	v_mfma_f32_16x16x32_bf16 v[42:45], v[156:159], v[194:197], v[42:45]
	v_mfma_f32_16x16x32_bf16 v[30:33], v[148:151], v[202:205], v[30:33]
	v_mfma_f32_16x16x32_bf16 v[26:29], v[156:159], v[202:205], v[26:29]
	v_mfma_f32_16x16x32_bf16 v[14:17], v[148:151], v[210:213], v[14:17]
	v_mfma_f32_16x16x32_bf16 v[10:13], v[156:159], v[210:213], v[10:13]
	v_mfma_f32_16x16x32_bf16 v[54:57], v[166:169], v[182:185], v[54:57]
	v_mfma_f32_16x16x32_bf16 v[50:53], v[174:177], v[182:185], v[50:53]
	v_mfma_f32_16x16x32_bf16 v[38:41], v[166:169], v[190:193], v[38:41]
	v_mfma_f32_16x16x32_bf16 v[34:37], v[174:177], v[190:193], v[34:37]
	v_mfma_f32_16x16x32_bf16 v[22:25], v[166:169], v[198:201], v[22:25]
	v_mfma_f32_16x16x32_bf16 v[18:21], v[174:177], v[198:201], v[18:21]
	v_mfma_f32_16x16x32_bf16 v[6:9], v[166:169], v[206:209], v[6:9]
	v_mfma_f32_16x16x32_bf16 v[2:5], v[174:177], v[206:209], v[2:5]
	v_mfma_f32_16x16x32_bf16 v[54:57], v[170:173], v[186:189], v[54:57]
	v_mfma_f32_16x16x32_bf16 v[50:53], v[178:181], v[186:189], v[50:53]
	v_mfma_f32_16x16x32_bf16 v[38:41], v[170:173], v[194:197], v[38:41]
	v_mfma_f32_16x16x32_bf16 v[34:37], v[178:181], v[194:197], v[34:37]
	v_mfma_f32_16x16x32_bf16 v[22:25], v[170:173], v[202:205], v[22:25]
	v_mfma_f32_16x16x32_bf16 v[18:21], v[178:181], v[202:205], v[18:21]
	v_mfma_f32_16x16x32_bf16 v[6:9], v[170:173], v[210:213], v[6:9]
	v_mfma_f32_16x16x32_bf16 v[2:5], v[178:181], v[210:213], v[2:5]
	s_setprio 0
	s_barrier
	s_add_i32 s30, 0, 0x18000
	v_add_u32_e32 v142, s30, v162
	s_add_i32 s31, 0, 0x1c000
	ds_read_b128 v[144:147], v142
	ds_read_b128 v[148:151], v142 offset:1024
	ds_read_b128 v[152:155], v142 offset:2048
	ds_read_b128 v[156:159], v142 offset:3072
	v_add_u32_e32 v142, s31, v162
	ds_read_b128 v[166:169], v142
	ds_read_b128 v[170:173], v142 offset:1024
	ds_read_b128 v[174:177], v142 offset:2048
	ds_read_b128 v[178:181], v142 offset:3072
	s_add_u32 s6, s6, 0x80000
	s_addc_u32 s7, s7, 0
	s_mov_b32 m0, s87
	v_lshl_add_u64 v[218:219], s[6:7], 0, v[134:135]
	ds_read_b128 v[182:185], v164 offset:32768
	ds_read_b128 v[186:189], v164 offset:33792
	ds_read_b128 v[190:193], v164 offset:34816
	ds_read_b128 v[194:197], v164 offset:35840
	ds_read_b128 v[198:201], v164 offset:36864
	ds_read_b128 v[202:205], v164 offset:37888
	ds_read_b128 v[206:209], v164 offset:38912
	ds_read_b128 v[210:213], v164 offset:39936
	global_load_lds_dwordx4 v[218:219], off
	s_mov_b32 m0, s91
	v_lshl_add_u64 v[218:219], s[6:7], 0, v[132:133]
	global_load_lds_dwordx4 v[218:219], off
	s_setprio 1
	s_waitcnt vmcnt(8) lgkmcnt(0)
	v_mfma_f32_16x16x32_bf16 v[126:129], v[144:147], v[182:185], v[126:129]
	v_mfma_f32_16x16x32_bf16 v[122:125], v[152:155], v[182:185], v[122:125]
	s_barrier
	v_mfma_f32_16x16x32_bf16 v[110:113], v[144:147], v[190:193], v[110:113]
	v_mfma_f32_16x16x32_bf16 v[106:109], v[152:155], v[190:193], v[106:109]
	v_mfma_f32_16x16x32_bf16 v[94:97], v[144:147], v[198:201], v[94:97]
	v_mfma_f32_16x16x32_bf16 v[90:93], v[152:155], v[198:201], v[90:93]
	v_mfma_f32_16x16x32_bf16 v[78:81], v[144:147], v[206:209], v[78:81]
	v_mfma_f32_16x16x32_bf16 v[74:77], v[152:155], v[206:209], v[74:77]
	v_mfma_f32_16x16x32_bf16 v[126:129], v[148:151], v[186:189], v[126:129]
	v_mfma_f32_16x16x32_bf16 v[122:125], v[156:159], v[186:189], v[122:125]
	v_mfma_f32_16x16x32_bf16 v[110:113], v[148:151], v[194:197], v[110:113]
	v_mfma_f32_16x16x32_bf16 v[106:109], v[156:159], v[194:197], v[106:109]
	v_mfma_f32_16x16x32_bf16 v[94:97], v[148:151], v[202:205], v[94:97]
	v_mfma_f32_16x16x32_bf16 v[90:93], v[156:159], v[202:205], v[90:93]
	v_mfma_f32_16x16x32_bf16 v[78:81], v[148:151], v[210:213], v[78:81]
	v_mfma_f32_16x16x32_bf16 v[74:77], v[156:159], v[210:213], v[74:77]
	v_mfma_f32_16x16x32_bf16 v[118:121], v[166:169], v[182:185], v[118:121]
	v_mfma_f32_16x16x32_bf16 v[114:117], v[174:177], v[182:185], v[114:117]
	v_mfma_f32_16x16x32_bf16 v[102:105], v[166:169], v[190:193], v[102:105]
	v_mfma_f32_16x16x32_bf16 v[98:101], v[174:177], v[190:193], v[98:101]
	v_mfma_f32_16x16x32_bf16 v[86:89], v[166:169], v[198:201], v[86:89]
	v_mfma_f32_16x16x32_bf16 v[82:85], v[174:177], v[198:201], v[82:85]
	v_mfma_f32_16x16x32_bf16 v[70:73], v[166:169], v[206:209], v[70:73]
	v_mfma_f32_16x16x32_bf16 v[66:69], v[174:177], v[206:209], v[66:69]
	v_mfma_f32_16x16x32_bf16 v[118:121], v[170:173], v[186:189], v[118:121]
	v_mfma_f32_16x16x32_bf16 v[114:117], v[178:181], v[186:189], v[114:117]
	v_mfma_f32_16x16x32_bf16 v[102:105], v[170:173], v[194:197], v[102:105]
	v_mfma_f32_16x16x32_bf16 v[98:101], v[178:181], v[194:197], v[98:101]
	v_mfma_f32_16x16x32_bf16 v[86:89], v[170:173], v[202:205], v[86:89]
	v_mfma_f32_16x16x32_bf16 v[82:85], v[178:181], v[202:205], v[82:85]
	v_mfma_f32_16x16x32_bf16 v[70:73], v[170:173], v[210:213], v[70:73]
	v_mfma_f32_16x16x32_bf16 v[66:69], v[178:181], v[210:213], v[66:69]
	s_setprio 0
	s_barrier
; #define PG8_STAGE(bufoff, gbase, voff) do { _Pragma("unroll") for (int _i = 0; _i < 2; ++_i) \
;         __builtin_amdgcn_global_load_lds((const unsigned*)((const char*)(gbase) + (voff)[_i]), (LAS unsigned*)(lds + (bufoff) + ldsw + _i * 8192), 16, 0, 0); } while (0)
; #define PG8_LDA(dst, b, h) do { _Pragma("unroll") for (int m = 0; m < 4; ++m) _Pragma("unroll") for (int k = 0; k < 2; ++k) dst[m][k] = *(const LAS bf16x8*)(lds + PG8_SA(b, h) + aoff + m * 2048 + k * 1024); } while (0)
; #define PG8_MMA(ai, bj, At, Bt) do { __builtin_amdgcn_s_setprio(1); _Pragma("unroll") for (int m = 0; m < 4; ++m) _Pragma("unroll") for (int n = 0; n < 2; ++n) _Pragma("unroll") for (int k = 0; k < 2; ++k) \
;         acc[ai][bj][m][n] = __builtin_amdgcn_mfma_f32_16x16x32_bf16(Bt[n][k], At[m][k], acc[ai][bj][m][n], 0, 0, 0); __builtin_amdgcn_s_setprio(0); } while (0)
; #define PG8_WAIT_V(n) asm volatile("s_waitcnt vmcnt(" #n ")" ::: "memory")
; #define PG8_WAIT_L(n) asm volatile("s_waitcnt lgkmcnt(" #n ")" ::: "memory")
; #define PG8_BAR __builtin_amdgcn_s_barrier()
; #define PG8_SCHED __builtin_amdgcn_sched_barrier(0)
; template <class Epi, int AMODE>
; __device__ __forceinline__ void gemm_phase(LAS unsigned char* lds, const Gemm g, const StaticOrder& S, const Epi& E, int stagger_us, int tid_in) {
;     ...
;             PG8_LDA(At, 1, 1); PG8_STAGE(PG8_SB(1, 0), b3, voffB); PG8_STAGE(PG8_SB(1, 1), b3 + hstepB, voffB); PG8_STAGE(PG8_SA(1, 0), a3, voffA);
;             PG8_WAIT_V(8); PG8_WAIT_L(0); PG8_BAR; PG8_MMA(1, 0, At, B0); PG8_MMA(1, 1, At, B1); PG8_BAR; PG8_SCHED;
;         }
	s_add_i32 s6, s30, s66
	v_lshl_add_u64 v[140:141], v[140:141], 0, s[74:75]
	s_mov_b32 m0, s6
	ds_read_b128 v[182:185], v164 offset:49152
	ds_read_b128 v[186:189], v164 offset:50176
	ds_read_b128 v[190:193], v164 offset:51200
	ds_read_b128 v[194:197], v164 offset:52224
	ds_read_b128 v[198:201], v164 offset:53248
	ds_read_b128 v[202:205], v164 offset:54272
	ds_read_b128 v[206:209], v164 offset:55296
	ds_read_b128 v[210:213], v164 offset:56320
	global_load_lds_dwordx4 v[140:141], off
	s_add_i32 m0, s6, 0x2000
	s_add_u32 s4, s4, 0x80080
	v_lshl_add_u64 v[140:141], v[160:161], 0, s[74:75]
	s_addc_u32 s5, s5, 0
	s_add_i32 s6, s31, s66
	global_load_lds_dwordx4 v[140:141], off
	s_mov_b32 m0, s6
	v_lshl_add_u64 v[140:141], s[4:5], 0, v[0:1]
	global_load_lds_dwordx4 v[140:141], off
	s_add_i32 m0, s6, 0x2000
	v_lshl_add_u64 v[140:141], s[4:5], 0, v[130:131]
	global_load_lds_dwordx4 v[140:141], off
	s_mov_b32 m0, s95
	v_lshl_add_u64 v[140:141], v[214:215], 0, s[74:75]
	global_load_lds_dwordx4 v[140:141], off
	s_mov_b32 m0, s96
	v_lshl_add_u64 v[140:141], v[216:217], 0, s[74:75]
	global_load_lds_dwordx4 v[140:141], off
	s_setprio 1
	s_waitcnt vmcnt(8) lgkmcnt(0)
	v_mfma_f32_16x16x32_bf16 v[62:65], v[144:147], v[182:185], v[62:65]
	v_mfma_f32_16x16x32_bf16 v[58:61], v[152:155], v[182:185], v[58:61]
	s_barrier
	v_mfma_f32_16x16x32_bf16 v[46:49], v[144:147], v[190:193], v[46:49]
	v_mfma_f32_16x16x32_bf16 v[42:45], v[152:155], v[190:193], v[42:45]
	v_mfma_f32_16x16x32_bf16 v[30:33], v[144:147], v[198:201], v[30:33]
	v_mfma_f32_16x16x32_bf16 v[26:29], v[152:155], v[198:201], v[26:29]
	v_mfma_f32_16x16x32_bf16 v[14:17], v[144:147], v[206:209], v[14:17]
	v_mfma_f32_16x16x32_bf16 v[10:13], v[152:155], v[206:209], v[10:13]
	v_mfma_f32_16x16x32_bf16 v[62:65], v[148:151], v[186:189], v[62:65]
	v_mfma_f32_16x16x32_bf16 v[58:61], v[156:159], v[186:189], v[58:61]
	v_mfma_f32_16x16x32_bf16 v[46:49], v[148:151], v[194:197], v[46:49]
	v_mfma_f32_16x16x32_bf16 v[42:45], v[156:159], v[194:197], v[42:45]
	v_mfma_f32_16x16x32_bf16 v[30:33], v[148:151], v[202:205], v[30:33]
	v_mfma_f32_16x16x32_bf16 v[26:29], v[156:159], v[202:205], v[26:29]
	v_mfma_f32_16x16x32_bf16 v[14:17], v[148:151], v[210:213], v[14:17]
	v_mfma_f32_16x16x32_bf16 v[10:13], v[156:159], v[210:213], v[10:13]
	v_mfma_f32_16x16x32_bf16 v[54:57], v[166:169], v[182:185], v[54:57]
	v_mfma_f32_16x16x32_bf16 v[50:53], v[174:177], v[182:185], v[50:53]
	v_mfma_f32_16x16x32_bf16 v[38:41], v[166:169], v[190:193], v[38:41]
	v_mfma_f32_16x16x32_bf16 v[34:37], v[174:177], v[190:193], v[34:37]
	v_mfma_f32_16x16x32_bf16 v[22:25], v[166:169], v[198:201], v[22:25]
	v_mfma_f32_16x16x32_bf16 v[18:21], v[174:177], v[198:201], v[18:21]
	v_mfma_f32_16x16x32_bf16 v[6:9], v[166:169], v[206:209], v[6:9]
	v_mfma_f32_16x16x32_bf16 v[2:5], v[174:177], v[206:209], v[2:5]
	v_mfma_f32_16x16x32_bf16 v[54:57], v[170:173], v[186:189], v[54:57]
	v_mfma_f32_16x16x32_bf16 v[50:53], v[178:181], v[186:189], v[50:53]
	v_mfma_f32_16x16x32_bf16 v[38:41], v[170:173], v[194:197], v[38:41]
	v_mfma_f32_16x16x32_bf16 v[34:37], v[178:181], v[194:197], v[34:37]
	v_mfma_f32_16x16x32_bf16 v[22:25], v[170:173], v[202:205], v[22:25]
	v_mfma_f32_16x16x32_bf16 v[18:21], v[178:181], v[202:205], v[18:21]
	v_mfma_f32_16x16x32_bf16 v[6:9], v[170:173], v[210:213], v[6:9]
	v_mfma_f32_16x16x32_bf16 v[2:5], v[178:181], v[210:213], v[2:5]
	s_setprio 0
	s_barrier
	s_add_i32 s29, s29, 2
	s_add_u32 s60, s60, 0x100
	s_addc_u32 s61, s61, 0
	s_add_u32 vcc_lo, vcc_lo, 0x100
	s_addc_u32 vcc_hi, vcc_hi, 0
	s_cmp_gt_u32 s29, 29
	s_cbranch_scc0 .LBB0_396
	s_and_b64 vcc, exec, s[46:47]
	s_cbranch_vccz .LBB0_399
	s_barrier

; #define PG8_STAGE(bufoff, gbase, voff) do { _Pragma("unroll") for (int _i = 0; _i < 2; ++_i) \
;         __builtin_amdgcn_global_load_lds((const unsigned*)((const char*)(gbase) + (voff)[_i]), (LAS unsigned*)(lds + (bufoff) + ldsw + _i * 8192), 16, 0, 0); } while (0)
; #define PG8_LDA(dst, b, h) do { _Pragma("unroll") for (int m = 0; m < 4; ++m) _Pragma("unroll") for (int k = 0; k < 2; ++k) dst[m][k] = *(const LAS bf16x8*)(lds + PG8_SA(b, h) + aoff + m * 2048 + k * 1024); } while (0)
; #define PG8_LDB(dst, b, h) do { _Pragma("unroll") for (int n = 0; n < 2; ++n) _Pragma("unroll") for (int k = 0; k < 2; ++k) dst[n][k] = *(const LAS bf16x8*)(lds + PG8_SB(b, h) + boff + n * 2048 + k * 1024); } while (0)
; #define PG8_MMA(ai, bj, At, Bt) do { __builtin_amdgcn_s_setprio(1); _Pragma("unroll") for (int m = 0; m < 4; ++m) _Pragma("unroll") for (int n = 0; n < 2; ++n) _Pragma("unroll") for (int k = 0; k < 2; ++k) \
;         acc[ai][bj][m][n] = __builtin_amdgcn_mfma_f32_16x16x32_bf16(Bt[n][k], At[m][k], acc[ai][bj][m][n], 0, 0, 0); __builtin_amdgcn_s_setprio(0); } while (0)
; #define PG8_WAIT_V(n) asm volatile("s_waitcnt vmcnt(" #n ")" ::: "memory")
; #define PG8_WAIT_L(n) asm volatile("s_waitcnt lgkmcnt(" #n ")" ::: "memory")
; #define PG8_BAR __builtin_amdgcn_s_barrier()
; #define PG8_SCHED __builtin_amdgcn_sched_barrier(0)
; template <class Epi, int AMODE>
; __device__ __forceinline__ void gemm_phase(LAS unsigned char* lds, const Gemm g, const StaticOrder& S, const Epi& E, int stagger_us, int tid_in) {
;     ...
;         for (int t = 0; t < nt; t += 2) {
;             const bool last = (t == nt - 2);
;             const char* a1 = cA + (size_t)(t + 1) * kstep;
;             const char* a2 = last ? nA : cA + (size_t)(t + 2) * kstep; const char* b2 = last ? nB : cB + (size_t)(t + 2) * kstep;
;             const char* a3 = a2 + kstep; const char* b3 = b2 + kstep;
;             PG8_LDB(B0, 0, 0); PG8_LDB(B1, 0, 1); PG8_SCHED; PG8_LDA(At, 0, 0); PG8_STAGE(PG8_SA(1, 1), a1 + hstepA, voffA);
;             PG8_WAIT_V(8); PG8_WAIT_L(0); PG8_BAR; PG8_MMA(0, 0, At, B0); PG8_MMA(0, 1, At, B1); PG8_BAR; PG8_SCHED;
;             PG8_LDA(At, 0, 1); PG8_STAGE(PG8_SB(0, 0), b2, voffB); PG8_STAGE(PG8_SB(0, 1), b2 + hstepB, voffB); PG8_STAGE(PG8_SA(0, 0), a2, voffA);
.LBB0_1199:
	s_add_u32 s4, s46, 0x100
	s_addc_u32 s5, s47, 0
	s_add_i32 s34, 0, 0x10000
	s_cmp_eq_u32 s31, 28
	s_cselect_b32 s95, s61, s5
	s_cselect_b32 s94, vcc_lo, s4
	s_cselect_b32 s7, s59, s30
	s_cselect_b32 s6, vcc_hi, s29
	s_add_i32 s35, 0, 0x14000
	v_add_u32_e32 v62, s34, v205
	v_add_u32_e32 v158, s35, v205
	ds_read_b128 v[50:53], v62
	ds_read_b128 v[54:57], v62 offset:1024
	ds_read_b128 v[58:61], v62 offset:2048
	ds_read_b128 v[62:65], v62 offset:3072
	ds_read_b128 v[146:149], v158
	ds_read_b128 v[150:153], v158 offset:1024
	ds_read_b128 v[154:157], v158 offset:2048
	ds_read_b128 v[158:161], v158 offset:3072
	v_lshl_add_u64 v[200:201], s[46:47], 0, v[176:177]
	s_add_i32 m0, s66, 0xc000
	ds_read_b128 v[162:165], v207
	ds_read_b128 v[166:169], v207 offset:1024
	ds_read_b128 v[170:173], v207 offset:2048
	ds_read_b128 v[180:183], v207 offset:3072
	ds_read_b128 v[184:187], v207 offset:4096
	ds_read_b128 v[188:191], v207 offset:5120
	ds_read_b128 v[192:195], v207 offset:6144
	ds_read_b128 v[196:199], v207 offset:7168
	global_load_lds_dwordx4 v[200:201], off
	s_add_i32 m0, s66, 0xe000
	v_lshl_add_u64 v[200:201], s[46:47], 0, v[178:179]
	global_load_lds_dwordx4 v[200:201], off
	s_setprio 1
	s_waitcnt vmcnt(8) lgkmcnt(0)
	v_mfma_f32_16x16x32_bf16 v[142:145], v[50:53], v[162:165], v[142:145]
	v_mfma_f32_16x16x32_bf16 v[138:141], v[58:61], v[162:165], v[138:141]
	s_barrier
	v_mfma_f32_16x16x32_bf16 v[126:129], v[50:53], v[170:173], v[126:129]
	v_mfma_f32_16x16x32_bf16 v[122:125], v[58:61], v[170:173], v[122:125]
	v_mfma_f32_16x16x32_bf16 v[110:113], v[50:53], v[184:187], v[110:113]
	v_mfma_f32_16x16x32_bf16 v[106:109], v[58:61], v[184:187], v[106:109]
	v_mfma_f32_16x16x32_bf16 v[94:97], v[50:53], v[192:195], v[94:97]
	v_mfma_f32_16x16x32_bf16 v[90:93], v[58:61], v[192:195], v[90:93]
	v_mfma_f32_16x16x32_bf16 v[142:145], v[54:57], v[166:169], v[142:145]
	v_mfma_f32_16x16x32_bf16 v[138:141], v[62:65], v[166:169], v[138:141]
	v_mfma_f32_16x16x32_bf16 v[126:129], v[54:57], v[180:183], v[126:129]
	v_mfma_f32_16x16x32_bf16 v[122:125], v[62:65], v[180:183], v[122:125]
	v_mfma_f32_16x16x32_bf16 v[110:113], v[54:57], v[188:191], v[110:113]
	v_mfma_f32_16x16x32_bf16 v[106:109], v[62:65], v[188:191], v[106:109]
	v_mfma_f32_16x16x32_bf16 v[94:97], v[54:57], v[196:199], v[94:97]
	v_mfma_f32_16x16x32_bf16 v[90:93], v[62:65], v[196:199], v[90:93]
	v_mfma_f32_16x16x32_bf16 v[134:137], v[146:149], v[162:165], v[134:137]
	v_mfma_f32_16x16x32_bf16 v[130:133], v[154:157], v[162:165], v[130:133]
	v_mfma_f32_16x16x32_bf16 v[118:121], v[146:149], v[170:173], v[118:121]
	v_mfma_f32_16x16x32_bf16 v[114:117], v[154:157], v[170:173], v[114:117]
	v_mfma_f32_16x16x32_bf16 v[102:105], v[146:149], v[184:187], v[102:105]
	v_mfma_f32_16x16x32_bf16 v[98:101], v[154:157], v[184:187], v[98:101]
	v_mfma_f32_16x16x32_bf16 v[86:89], v[146:149], v[192:195], v[86:89]
	v_mfma_f32_16x16x32_bf16 v[82:85], v[154:157], v[192:195], v[82:85]
	v_mfma_f32_16x16x32_bf16 v[134:137], v[150:153], v[166:169], v[134:137]
	v_mfma_f32_16x16x32_bf16 v[130:133], v[158:161], v[166:169], v[130:133]
	v_mfma_f32_16x16x32_bf16 v[118:121], v[150:153], v[180:183], v[118:121]
	v_mfma_f32_16x16x32_bf16 v[114:117], v[158:161], v[180:183], v[114:117]
	v_mfma_f32_16x16x32_bf16 v[102:105], v[150:153], v[188:191], v[102:105]
	v_mfma_f32_16x16x32_bf16 v[98:101], v[158:161], v[188:191], v[98:101]
	v_mfma_f32_16x16x32_bf16 v[86:89], v[150:153], v[196:199], v[86:89]
	v_mfma_f32_16x16x32_bf16 v[82:85], v[158:161], v[196:199], v[82:85]
	s_setprio 0
	s_barrier
	s_add_i32 s34, s34, s13
	v_lshl_add_u64 v[200:201], s[6:7], 0, v[0:1]
	s_mov_b32 m0, s34
	ds_read_b128 v[162:165], v207 offset:16384
	ds_read_b128 v[166:169], v207 offset:17408
	ds_read_b128 v[170:173], v207 offset:18432
	ds_read_b128 v[180:183], v207 offset:19456
	ds_read_b128 v[184:187], v207 offset:20480
	ds_read_b128 v[188:191], v207 offset:21504
	ds_read_b128 v[192:195], v207 offset:22528
	ds_read_b128 v[196:199], v207 offset:23552
	global_load_lds_dwordx4 v[200:201], off
	s_add_i32 m0, s34, 0x2000
	s_add_u32 s46, s6, 0x80000
	v_lshl_add_u64 v[202:203], s[6:7], 0, v[174:175]
	s_addc_u32 s47, s7, 0
	s_add_i32 s34, s35, s13
	global_load_lds_dwordx4 v[202:203], off
	v_lshl_add_u64 v[208:209], s[46:47], 0, v[0:1]
	s_mov_b32 m0, s34
	v_lshl_add_u64 v[210:211], s[94:95], 0, v[174:175]
	global_load_lds_dwordx4 v[208:209], off
	s_add_i32 m0, s34, 0x2000
	v_lshl_add_u64 v[208:209], s[46:47], 0, v[174:175]
	global_load_lds_dwordx4 v[208:209], off
	s_mov_b32 m0, s66
	v_lshl_add_u64 v[208:209], s[94:95], 0, v[0:1]
	global_load_lds_dwordx4 v[208:209], off
	s_mov_b32 m0, s67
	s_nop 0
	global_load_lds_dwordx4 v[210:211], off
	s_setprio 1
	s_waitcnt vmcnt(8) lgkmcnt(0)
	v_mfma_f32_16x16x32_bf16 v[78:81], v[50:53], v[162:165], v[78:81]
	v_mfma_f32_16x16x32_bf16 v[74:77], v[58:61], v[162:165], v[74:77]
	s_barrier
; #define PG8_STAGE(bufoff, gbase, voff) do { _Pragma("unroll") for (int _i = 0; _i < 2; ++_i) \
;         __builtin_amdgcn_global_load_lds((const unsigned*)((const char*)(gbase) + (voff)[_i]), (LAS unsigned*)(lds + (bufoff) + ldsw + _i * 8192), 16, 0, 0); } while (0)
; #define PG8_LDA(dst, b, h) do { _Pragma("unroll") for (int m = 0; m < 4; ++m) _Pragma("unroll") for (int k = 0; k < 2; ++k) dst[m][k] = *(const LAS bf16x8*)(lds + PG8_SA(b, h) + aoff + m * 2048 + k * 1024); } while (0)
; #define PG8_LDB(dst, b, h) do { _Pragma("unroll") for (int n = 0; n < 2; ++n) _Pragma("unroll") for (int k = 0; k < 2; ++k) dst[n][k] = *(const LAS bf16x8*)(lds + PG8_SB(b, h) + boff + n * 2048 + k * 1024); } while (0)
; #define PG8_MMA(ai, bj, At, Bt) do { __builtin_amdgcn_s_setprio(1); _Pragma("unroll") for (int m = 0; m < 4; ++m) _Pragma("unroll") for (int n = 0; n < 2; ++n) _Pragma("unroll") for (int k = 0; k < 2; ++k) \
;         acc[ai][bj][m][n] = __builtin_amdgcn_mfma_f32_16x16x32_bf16(Bt[n][k], At[m][k], acc[ai][bj][m][n], 0, 0, 0); __builtin_amdgcn_s_setprio(0); } while (0)
; #define PG8_WAIT_V(n) asm volatile("s_waitcnt vmcnt(" #n ")" ::: "memory")
; #define PG8_WAIT_L(n) asm volatile("s_waitcnt lgkmcnt(" #n ")" ::: "memory")
; #define PG8_BAR __builtin_amdgcn_s_barrier()
; #define PG8_SCHED __builtin_amdgcn_sched_barrier(0)
; template <class Epi, int AMODE>
; __device__ __forceinline__ void gemm_phase(LAS unsigned char* lds, const Gemm g, const StaticOrder& S, const Epi& E, int stagger_us, int tid_in) {
;     ...
;             PG8_WAIT_V(8); PG8_WAIT_L(0); PG8_BAR; PG8_MMA(1, 0, At, B0); PG8_MMA(1, 1, At, B1); PG8_BAR; PG8_SCHED;
;             PG8_LDB(B0, 1, 0); PG8_LDB(B1, 1, 1); PG8_SCHED; PG8_LDA(At, 1, 0); PG8_STAGE(PG8_SA(0, 1), a2 + hstepA, voffA);
;             PG8_WAIT_V(8); PG8_WAIT_L(0); PG8_BAR; PG8_MMA(0, 0, At, B0); PG8_MMA(0, 1, At, B1); PG8_BAR; PG8_SCHED;
;             PG8_LDA(At, 1, 1); PG8_STAGE(PG8_SB(1, 0), b3, voffB); PG8_STAGE(PG8_SB(1, 1), b3 + hstepB, voffB); PG8_STAGE(PG8_SA(1, 0), a3, voffA);
	v_mfma_f32_16x16x32_bf16 v[46:49], v[50:53], v[170:173], v[46:49]
	v_mfma_f32_16x16x32_bf16 v[42:45], v[58:61], v[170:173], v[42:45]
	v_mfma_f32_16x16x32_bf16 v[30:33], v[50:53], v[184:187], v[30:33]
	v_mfma_f32_16x16x32_bf16 v[26:29], v[58:61], v[184:187], v[26:29]
	v_mfma_f32_16x16x32_bf16 v[14:17], v[50:53], v[192:195], v[14:17]
	v_mfma_f32_16x16x32_bf16 v[10:13], v[58:61], v[192:195], v[10:13]
	v_mfma_f32_16x16x32_bf16 v[78:81], v[54:57], v[166:169], v[78:81]
	v_mfma_f32_16x16x32_bf16 v[74:77], v[62:65], v[166:169], v[74:77]
	v_mfma_f32_16x16x32_bf16 v[46:49], v[54:57], v[180:183], v[46:49]
	v_mfma_f32_16x16x32_bf16 v[42:45], v[62:65], v[180:183], v[42:45]
	v_mfma_f32_16x16x32_bf16 v[30:33], v[54:57], v[188:191], v[30:33]
	v_mfma_f32_16x16x32_bf16 v[26:29], v[62:65], v[188:191], v[26:29]
	v_mfma_f32_16x16x32_bf16 v[14:17], v[54:57], v[196:199], v[14:17]
	v_mfma_f32_16x16x32_bf16 v[10:13], v[62:65], v[196:199], v[10:13]
	v_mfma_f32_16x16x32_bf16 v[38:41], v[146:149], v[170:173], v[38:41]
	v_mfma_f32_16x16x32_bf16 v[34:37], v[154:157], v[170:173], v[34:37]
	v_mfma_f32_16x16x32_bf16 v[22:25], v[146:149], v[184:187], v[22:25]
	v_mfma_f32_16x16x32_bf16 v[18:21], v[154:157], v[184:187], v[18:21]
	v_mfma_f32_16x16x32_bf16 v[6:9], v[146:149], v[192:195], v[6:9]
	v_mfma_f32_16x16x32_bf16 v[2:5], v[154:157], v[192:195], v[2:5]
	v_mfma_f32_16x16x32_bf16 v[50:53], v[146:149], v[162:165], v[70:73]
	v_mfma_f32_16x16x32_bf16 v[54:57], v[154:157], v[162:165], v[66:69]
	v_mfma_f32_16x16x32_bf16 v[38:41], v[150:153], v[180:183], v[38:41]
	v_mfma_f32_16x16x32_bf16 v[34:37], v[158:161], v[180:183], v[34:37]
	v_mfma_f32_16x16x32_bf16 v[22:25], v[150:153], v[188:191], v[22:25]
	v_mfma_f32_16x16x32_bf16 v[18:21], v[158:161], v[188:191], v[18:21]
	v_mfma_f32_16x16x32_bf16 v[6:9], v[150:153], v[196:199], v[6:9]
	v_mfma_f32_16x16x32_bf16 v[2:5], v[158:161], v[196:199], v[2:5]
	v_mfma_f32_16x16x32_bf16 v[50:53], v[150:153], v[166:169], v[50:53]
	v_mfma_f32_16x16x32_bf16 v[54:57], v[158:161], v[166:169], v[54:57]
	s_setprio 0
	s_barrier
	s_add_i32 s34, 0, 0x18000
	s_add_i32 s35, 0, 0x1c000
	v_add_u32_e32 v70, s34, v205
	v_add_u32_e32 v158, s35, v205
	ds_read_b128 v[58:61], v70
	ds_read_b128 v[62:65], v70 offset:1024
	ds_read_b128 v[66:69], v70 offset:2048
	ds_read_b128 v[70:73], v70 offset:3072
	ds_read_b128 v[146:149], v158
	ds_read_b128 v[150:153], v158 offset:1024
	ds_read_b128 v[154:157], v158 offset:2048
	ds_read_b128 v[158:161], v158 offset:3072
	s_add_u32 s46, s94, 0x80000
	s_addc_u32 s47, s95, 0
	s_mov_b32 m0, s69
	v_lshl_add_u64 v[212:213], s[46:47], 0, v[0:1]
	ds_read_b128 v[162:165], v207 offset:32768
	ds_read_b128 v[166:169], v207 offset:33792
	ds_read_b128 v[170:173], v207 offset:34816
	ds_read_b128 v[180:183], v207 offset:35840
	ds_read_b128 v[184:187], v207 offset:36864
	ds_read_b128 v[188:191], v207 offset:37888
	ds_read_b128 v[192:195], v207 offset:38912
	ds_read_b128 v[196:199], v207 offset:39936
	global_load_lds_dwordx4 v[212:213], off
	s_mov_b32 m0, s72
	v_lshl_add_u64 v[212:213], s[46:47], 0, v[174:175]
	global_load_lds_dwordx4 v[212:213], off
	s_setprio 1
	s_waitcnt vmcnt(8) lgkmcnt(0)
	v_mfma_f32_16x16x32_bf16 v[142:145], v[58:61], v[162:165], v[142:145]
	v_mfma_f32_16x16x32_bf16 v[138:141], v[66:69], v[162:165], v[138:141]
	s_barrier
	v_mfma_f32_16x16x32_bf16 v[126:129], v[58:61], v[170:173], v[126:129]
	v_mfma_f32_16x16x32_bf16 v[122:125], v[66:69], v[170:173], v[122:125]
	v_mfma_f32_16x16x32_bf16 v[110:113], v[58:61], v[184:187], v[110:113]
	v_mfma_f32_16x16x32_bf16 v[106:109], v[66:69], v[184:187], v[106:109]
	v_mfma_f32_16x16x32_bf16 v[94:97], v[58:61], v[192:195], v[94:97]
	v_mfma_f32_16x16x32_bf16 v[90:93], v[66:69], v[192:195], v[90:93]
	v_mfma_f32_16x16x32_bf16 v[142:145], v[62:65], v[166:169], v[142:145]
	v_mfma_f32_16x16x32_bf16 v[138:141], v[70:73], v[166:169], v[138:141]
	v_mfma_f32_16x16x32_bf16 v[126:129], v[62:65], v[180:183], v[126:129]
	v_mfma_f32_16x16x32_bf16 v[122:125], v[70:73], v[180:183], v[122:125]
	v_mfma_f32_16x16x32_bf16 v[110:113], v[62:65], v[188:191], v[110:113]
	v_mfma_f32_16x16x32_bf16 v[106:109], v[70:73], v[188:191], v[106:109]
	v_mfma_f32_16x16x32_bf16 v[94:97], v[62:65], v[196:199], v[94:97]
	v_mfma_f32_16x16x32_bf16 v[90:93], v[70:73], v[196:199], v[90:93]
	v_mfma_f32_16x16x32_bf16 v[134:137], v[146:149], v[162:165], v[134:137]
	v_mfma_f32_16x16x32_bf16 v[130:133], v[154:157], v[162:165], v[130:133]
	v_mfma_f32_16x16x32_bf16 v[118:121], v[146:149], v[170:173], v[118:121]
	v_mfma_f32_16x16x32_bf16 v[114:117], v[154:157], v[170:173], v[114:117]
	v_mfma_f32_16x16x32_bf16 v[102:105], v[146:149], v[184:187], v[102:105]
	v_mfma_f32_16x16x32_bf16 v[98:101], v[154:157], v[184:187], v[98:101]
	v_mfma_f32_16x16x32_bf16 v[86:89], v[146:149], v[192:195], v[86:89]
	v_mfma_f32_16x16x32_bf16 v[82:85], v[154:157], v[192:195], v[82:85]
	v_mfma_f32_16x16x32_bf16 v[134:137], v[150:153], v[166:169], v[134:137]
	v_mfma_f32_16x16x32_bf16 v[130:133], v[158:161], v[166:169], v[130:133]
	v_mfma_f32_16x16x32_bf16 v[118:121], v[150:153], v[180:183], v[118:121]
	v_mfma_f32_16x16x32_bf16 v[114:117], v[158:161], v[180:183], v[114:117]
	v_mfma_f32_16x16x32_bf16 v[102:105], v[150:153], v[188:191], v[102:105]
	v_mfma_f32_16x16x32_bf16 v[98:101], v[158:161], v[188:191], v[98:101]
	v_mfma_f32_16x16x32_bf16 v[86:89], v[150:153], v[196:199], v[86:89]
	v_mfma_f32_16x16x32_bf16 v[82:85], v[158:161], v[196:199], v[82:85]
	s_setprio 0
	s_barrier
; #define PG8_STAGE(bufoff, gbase, voff) do { _Pragma("unroll") for (int _i = 0; _i < 2; ++_i) \
;         __builtin_amdgcn_global_load_lds((const unsigned*)((const char*)(gbase) + (voff)[_i]), (LAS unsigned*)(lds + (bufoff) + ldsw + _i * 8192), 16, 0, 0); } while (0)
; #define PG8_LDA(dst, b, h) do { _Pragma("unroll") for (int m = 0; m < 4; ++m) _Pragma("unroll") for (int k = 0; k < 2; ++k) dst[m][k] = *(const LAS bf16x8*)(lds + PG8_SA(b, h) + aoff + m * 2048 + k * 1024); } while (0)
; #define PG8_MMA(ai, bj, At, Bt) do { __builtin_amdgcn_s_setprio(1); _Pragma("unroll") for (int m = 0; m < 4; ++m) _Pragma("unroll") for (int n = 0; n < 2; ++n) _Pragma("unroll") for (int k = 0; k < 2; ++k) \
;         acc[ai][bj][m][n] = __builtin_amdgcn_mfma_f32_16x16x32_bf16(Bt[n][k], At[m][k], acc[ai][bj][m][n], 0, 0, 0); __builtin_amdgcn_s_setprio(0); } while (0)
; #define PG8_WAIT_V(n) asm volatile("s_waitcnt vmcnt(" #n ")" ::: "memory")
; #define PG8_WAIT_L(n) asm volatile("s_waitcnt lgkmcnt(" #n ")" ::: "memory")
; #define PG8_BAR __builtin_amdgcn_s_barrier()
; #define PG8_SCHED __builtin_amdgcn_sched_barrier(0)
; template <class Epi, int AMODE>
; __device__ __forceinline__ void gemm_phase(LAS unsigned char* lds, const Gemm g, const StaticOrder& S, const Epi& E, int stagger_us, int tid_in) {
;     ...
;             PG8_LDA(At, 1, 1); PG8_STAGE(PG8_SB(1, 0), b3, voffB); PG8_STAGE(PG8_SB(1, 1), b3 + hstepB, voffB); PG8_STAGE(PG8_SA(1, 0), a3, voffA);
;             PG8_WAIT_V(8); PG8_WAIT_L(0); PG8_BAR; PG8_MMA(1, 0, At, B0); PG8_MMA(1, 1, At, B1); PG8_BAR; PG8_SCHED;
;         }
	s_add_i32 s34, s34, s13
	v_lshl_add_u64 v[200:201], v[200:201], 0, s[74:75]
	s_mov_b32 m0, s34
	ds_read_b128 v[162:165], v207 offset:49152
	ds_read_b128 v[166:169], v207 offset:50176
	ds_read_b128 v[170:173], v207 offset:51200
	ds_read_b128 v[180:183], v207 offset:52224
	ds_read_b128 v[184:187], v207 offset:53248
	ds_read_b128 v[188:191], v207 offset:54272
	ds_read_b128 v[192:195], v207 offset:55296
	ds_read_b128 v[196:199], v207 offset:56320
	global_load_lds_dwordx4 v[200:201], off
	s_add_i32 m0, s34, 0x2000
	s_add_u32 s6, s6, 0x80080
	v_lshl_add_u64 v[200:201], v[202:203], 0, s[74:75]
	s_addc_u32 s7, s7, 0
	s_add_i32 s34, s35, s13
	global_load_lds_dwordx4 v[200:201], off
	s_mov_b32 m0, s34
	v_lshl_add_u64 v[200:201], s[6:7], 0, v[0:1]
	global_load_lds_dwordx4 v[200:201], off
	s_add_i32 m0, s34, 0x2000
	v_lshl_add_u64 v[200:201], s[6:7], 0, v[174:175]
	global_load_lds_dwordx4 v[200:201], off
	s_mov_b32 m0, s91
	v_lshl_add_u64 v[200:201], v[208:209], 0, s[74:75]
	global_load_lds_dwordx4 v[200:201], off
	s_mov_b32 m0, s96
	v_lshl_add_u64 v[200:201], v[210:211], 0, s[74:75]
	global_load_lds_dwordx4 v[200:201], off
	s_setprio 1
	s_waitcnt vmcnt(8) lgkmcnt(0)
	v_mfma_f32_16x16x32_bf16 v[78:81], v[58:61], v[162:165], v[78:81]
	v_mfma_f32_16x16x32_bf16 v[74:77], v[66:69], v[162:165], v[74:77]
	s_barrier
	v_mfma_f32_16x16x32_bf16 v[46:49], v[58:61], v[170:173], v[46:49]
	v_mfma_f32_16x16x32_bf16 v[42:45], v[66:69], v[170:173], v[42:45]
	v_mfma_f32_16x16x32_bf16 v[30:33], v[58:61], v[184:187], v[30:33]
	v_mfma_f32_16x16x32_bf16 v[26:29], v[66:69], v[184:187], v[26:29]
	v_mfma_f32_16x16x32_bf16 v[14:17], v[58:61], v[192:195], v[14:17]
	v_mfma_f32_16x16x32_bf16 v[10:13], v[66:69], v[192:195], v[10:13]
	v_mfma_f32_16x16x32_bf16 v[78:81], v[62:65], v[166:169], v[78:81]
	v_mfma_f32_16x16x32_bf16 v[74:77], v[70:73], v[166:169], v[74:77]
	v_mfma_f32_16x16x32_bf16 v[46:49], v[62:65], v[180:183], v[46:49]
	v_mfma_f32_16x16x32_bf16 v[42:45], v[70:73], v[180:183], v[42:45]
	v_mfma_f32_16x16x32_bf16 v[30:33], v[62:65], v[188:191], v[30:33]
	v_mfma_f32_16x16x32_bf16 v[26:29], v[70:73], v[188:191], v[26:29]
	v_mfma_f32_16x16x32_bf16 v[14:17], v[62:65], v[196:199], v[14:17]
	v_mfma_f32_16x16x32_bf16 v[10:13], v[70:73], v[196:199], v[10:13]
	v_mfma_f32_16x16x32_bf16 v[50:53], v[146:149], v[162:165], v[50:53]
	v_mfma_f32_16x16x32_bf16 v[70:73], v[150:153], v[166:169], v[50:53]
	v_mfma_f32_16x16x32_bf16 v[50:53], v[154:157], v[162:165], v[54:57]
	v_mfma_f32_16x16x32_bf16 v[38:41], v[146:149], v[170:173], v[38:41]
	v_mfma_f32_16x16x32_bf16 v[34:37], v[154:157], v[170:173], v[34:37]
	v_mfma_f32_16x16x32_bf16 v[22:25], v[146:149], v[184:187], v[22:25]
	v_mfma_f32_16x16x32_bf16 v[18:21], v[154:157], v[184:187], v[18:21]
	v_mfma_f32_16x16x32_bf16 v[6:9], v[146:149], v[192:195], v[6:9]
	v_mfma_f32_16x16x32_bf16 v[2:5], v[154:157], v[192:195], v[2:5]
	v_mfma_f32_16x16x32_bf16 v[66:69], v[158:161], v[166:169], v[50:53]
	v_mfma_f32_16x16x32_bf16 v[38:41], v[150:153], v[180:183], v[38:41]
	v_mfma_f32_16x16x32_bf16 v[34:37], v[158:161], v[180:183], v[34:37]
	v_mfma_f32_16x16x32_bf16 v[22:25], v[150:153], v[188:191], v[22:25]
	v_mfma_f32_16x16x32_bf16 v[18:21], v[158:161], v[188:191], v[18:21]
	v_mfma_f32_16x16x32_bf16 v[6:9], v[150:153], v[196:199], v[6:9]
	v_mfma_f32_16x16x32_bf16 v[2:5], v[158:161], v[196:199], v[2:5]
	s_setprio 0
	s_barrier
	s_add_i32 s31, s31, 2
	s_add_u32 s29, s29, 0x100
	s_addc_u32 s30, s30, 0
	s_cmp_gt_u32 s31, 29
	s_mov_b64 s[46:47], s[4:5]
	s_cbranch_scc0 .LBB0_1199
	s_and_b64 vcc, exec, s[56:57]
	s_cbranch_vccz .LBB0_1202
	s_barrier

; #define PG8_STAGE(bufoff, gbase, voff) do { _Pragma("unroll") for (int _i = 0; _i < 2; ++_i) \
;         __builtin_amdgcn_global_load_lds((const unsigned*)((const char*)(gbase) + (voff)[_i]), (LAS unsigned*)(lds + (bufoff) + ldsw + _i * 8192), 16, 0, 0); } while (0)
; #define PG8_WAIT_V(n) asm volatile("s_waitcnt vmcnt(" #n ")" ::: "memory")
; #define PG8_WAIT_L(n) asm volatile("s_waitcnt lgkmcnt(" #n ")" ::: "memory")
; #define PG8_BAR __builtin_amdgcn_s_barrier()
; template <class Epi, int AMODE>
; __device__ __forceinline__ void gemm_phase(LAS unsigned char* lds, const Gemm g, const StaticOrder& S, const Epi& E, int stagger_us, int tid_in) {
;     ...
;         const bool has_next = S.next(ui + 1, nxt);
;         const char* nA = has_next ? Abase + (size_t)nxt.pm * tstepA : cA; const char* nB = has_next ? (const char*)g.Bt + (size_t)nxt.pn * tstepB : cB;
;         for (int t = 0; t < nt; t += 2) {
;             const bool last = (t == nt - 2);
;             const char* a1 = cA + (size_t)(t + 1) * kstep;
;             const char* a2 = last ? nA : cA + (size_t)(t + 2) * kstep; const char* b2 = last ? nB : cB + (size_t)(t + 2) * kstep;
;             const char* a3 = a2 + kstep; const char* b3 = b2 + kstep;
;             PG8_LDB(B0, 0, 0); PG8_LDB(B1, 0, 1); PG8_SCHED; PG8_LDA(At, 0, 0); PG8_STAGE(PG8_SA(1, 1), a1 + hstepA, voffA);
;             PG8_WAIT_V(8); PG8_WAIT_L(0); PG8_BAR; PG8_MMA(0, 0, At, B0); PG8_MMA(0, 1, At, B1); PG8_BAR; PG8_SCHED;
;     __device__ __forceinline__ void operator()(f32x4 (&acc)[2][2][4][2], const Unit& u, int wr, int wc, int fr, int fq) const {
;     ...
;         const int tok0 = 252 * u.pm + 126 * wr - 1;
;         {
;             const int tq = tok0 + 8 * fr; const int tA = tq < 0 ? 0 : (tq > TOK - 1 ? TOK - 1 : tq), tB = (tq + 7) > TOK - 1 ? TOK - 1 : (tq + 7);
;             const int bA = batch_of(tA), bB = batch_of(tB); const bool same = __all(bA == bB);
;             const float* bp0 = bias + 256 * u.pn + 32 * wc + 8 * fq;
;             f32x4 bvA[2][2]; float sq[8];
; #pragma unroll
;             for (int am = 0; am < 8; ++am) { int tok = tq + am; tok = tok < 0 ? 0 : (tok > TOK - 1 ? TOK - 1 : tok); sq[am] = LDG(float, ssq + tok); }
; #pragma unroll
;             for (int bj = 0; bj < 2; ++bj)
; #pragma unroll
;                 for (int n = 0; n < 2; ++n) bvA[bj][n] = LDG(f32x4, bp0 + (size_t)bA * (2 * DFF) + bj * HALF + 4 * n);
.LBB0_1298:
	s_ashr_i32 s47, s46, 31
	s_lshl_b64 s[6:7], s[46:47], 20
	s_add_u32 s96, s9, s6
	s_addc_u32 s97, s72, s7
	s_and_b64 s[6:7], s[42:43], exec
	s_cselect_b32 s27, s97, s5
	s_cselect_b32 s28, s96, s4
	s_add_u32 s29, s4, 0x100
	v_mov_b32_e32 v2, 0
	s_addc_u32 s30, s5, 0
	s_mov_b32 s31, -2
	s_mul_i32 s6, s26, 0xfc
	v_add_u32_e32 v222, s6, v197
	v_med3_i32 v240, v222, 0, v238
	v_add_u32_e32 v241, 0xffffe000, v240
	v_lshrrev_b32_e32 v241, 12, v241
	v_add_u32_e32 v241, 4, v241
	v_lshrrev_b32_e32 v242, 11, v240
	v_mov_b32_e32 v243, 0x2000
	v_cmp_gt_i32_e64 s[6:7], v243, v222
	s_nop 1
	v_cndmask_b32_e64 v241, v241, v242, s[6:7]
	s_lshl_b32 s6, s92, 8
	s_ashr_i32 s7, s6, 31
	v_lshl_add_u64 v[236:237], s[6:7], 2, v[184:185]
	v_mad_u64_u32 v[236:237], s[6:7], v241, s15, v[236:237]
	v_med3_i32 v224, v222, 0, v238
	v_lshlrev_b32_e32 v224, 2, v224
	global_load_dword v224, v224, s[56:57]
	v_add_u32_e32 v228, 1, v222
	v_med3_i32 v228, v228, 0, v238
	v_lshlrev_b32_e32 v228, 2, v228
	global_load_dword v228, v228, s[56:57]
	v_add_u32_e32 v231, 2, v222
	v_med3_i32 v231, v231, 0, v238
	v_lshlrev_b32_e32 v231, 2, v231
	global_load_dword v231, v231, s[56:57]
	v_add_u32_e32 v233, 3, v222
	v_med3_i32 v233, v233, 0, v238
	v_lshlrev_b32_e32 v233, 2, v233
	global_load_dword v233, v233, s[56:57]
	v_add_u32_e32 v234, 4, v222
	v_med3_i32 v234, v234, 0, v238
	v_lshlrev_b32_e32 v234, 2, v234
	global_load_dword v234, v234, s[56:57]
	v_add_u32_e32 v239, 5, v222
	v_med3_i32 v239, v239, 0, v238
	v_lshlrev_b32_e32 v239, 2, v239
	global_load_dword v239, v239, s[56:57]
	v_add_u32_e32 v252, 6, v222
	v_med3_i32 v252, v252, 0, v238
	v_lshlrev_b32_e32 v252, 2, v252
	global_load_dword v252, v252, s[56:57]
	v_add_u32_e32 v253, 7, v222
	v_med3_i32 v253, v253, 0, v238
	v_lshlrev_b32_e32 v253, 2, v253
	global_load_dword v253, v253, s[56:57]
	global_load_dwordx4 v[240:243], v[236:237], off
	global_load_dwordx4 v[244:247], v[236:237], off offset:16
	global_load_dwordx4 v[248:251], v[236:237], off offset:512
	global_load_dwordx2 v[222:223], v[236:237], off offset:528
	s_nop 0
	global_load_dwordx2 v[236:237], v[236:237], off offset:536
	v_mov_b32_e32 v3, v2
	v_mov_b32_e32 v4, v2
	v_mov_b32_e32 v5, v2
	v_mov_b32_e32 v14, v2
	v_mov_b32_e32 v15, v2
	v_mov_b32_e32 v16, v2
	v_mov_b32_e32 v17, v2
	v_mov_b32_e32 v10, v2
	v_mov_b32_e32 v11, v2
	v_mov_b32_e32 v12, v2
	v_mov_b32_e32 v13, v2
	v_mov_b32_e32 v26, v2
	v_mov_b32_e32 v27, v2
	v_mov_b32_e32 v28, v2
	v_mov_b32_e32 v29, v2
	v_mov_b32_e32 v6, v2
	v_mov_b32_e32 v7, v2
	v_mov_b32_e32 v8, v2
	v_mov_b32_e32 v9, v2
	v_mov_b32_e32 v42, v2
	v_mov_b32_e32 v43, v2
	v_mov_b32_e32 v44, v2
	v_mov_b32_e32 v45, v2
	v_mov_b32_e32 v30, v2
	v_mov_b32_e32 v31, v2
	v_mov_b32_e32 v32, v2
	v_mov_b32_e32 v33, v2
	v_mov_b32_e32 v58, v2
	v_mov_b32_e32 v59, v2
	v_mov_b32_e32 v60, v2
	v_mov_b32_e32 v61, v2
	v_mov_b32_e32 v74, v2
	v_mov_b32_e32 v75, v2
	v_mov_b32_e32 v76, v2
	v_mov_b32_e32 v77, v2
	v_mov_b32_e32 v22, v2
	v_mov_b32_e32 v23, v2
	v_mov_b32_e32 v24, v2
	v_mov_b32_e32 v25, v2
	v_mov_b32_e32 v34, v2
	v_mov_b32_e32 v35, v2
	v_mov_b32_e32 v36, v2
	v_mov_b32_e32 v37, v2
	v_mov_b32_e32 v18, v2
	v_mov_b32_e32 v19, v2
	v_mov_b32_e32 v20, v2
	v_mov_b32_e32 v21, v2
	v_mov_b32_e32 v50, v2
	v_mov_b32_e32 v51, v2
	v_mov_b32_e32 v52, v2
	v_mov_b32_e32 v53, v2
	v_mov_b32_e32 v38, v2
	v_mov_b32_e32 v39, v2
	v_mov_b32_e32 v40, v2
	v_mov_b32_e32 v41, v2
	v_mov_b32_e32 v46, v2
	v_mov_b32_e32 v47, v2
	v_mov_b32_e32 v48, v2
	v_mov_b32_e32 v49, v2
	v_mov_b32_e32 v54, v2
	v_mov_b32_e32 v55, v2
	v_mov_b32_e32 v56, v2
	v_mov_b32_e32 v57, v2
	v_mov_b32_e32 v66, v2
	v_mov_b32_e32 v67, v2
	v_mov_b32_e32 v68, v2
	v_mov_b32_e32 v69, v2
	v_mov_b32_e32 v78, v2
	v_mov_b32_e32 v79, v2
	v_mov_b32_e32 v80, v2
	v_mov_b32_e32 v81, v2
	v_mov_b32_e32 v62, v2
	v_mov_b32_e32 v63, v2
	v_mov_b32_e32 v64, v2
	v_mov_b32_e32 v65, v2
	v_mov_b32_e32 v70, v2
	v_mov_b32_e32 v71, v2
	v_mov_b32_e32 v72, v2
	v_mov_b32_e32 v73, v2
	v_mov_b32_e32 v86, v2
	v_mov_b32_e32 v87, v2
	v_mov_b32_e32 v88, v2
	v_mov_b32_e32 v89, v2
	v_mov_b32_e32 v94, v2
	v_mov_b32_e32 v95, v2
	v_mov_b32_e32 v96, v2
	v_mov_b32_e32 v97, v2
	v_mov_b32_e32 v98, v2
	v_mov_b32_e32 v99, v2
	v_mov_b32_e32 v100, v2
	v_mov_b32_e32 v101, v2
	v_mov_b32_e32 v106, v2
	v_mov_b32_e32 v107, v2
	v_mov_b32_e32 v108, v2
	v_mov_b32_e32 v109, v2
	v_mov_b32_e32 v82, v2
	v_mov_b32_e32 v83, v2
	v_mov_b32_e32 v84, v2
	v_mov_b32_e32 v85, v2
	v_mov_b32_e32 v90, v2
	v_mov_b32_e32 v91, v2
	v_mov_b32_e32 v92, v2
	v_mov_b32_e32 v93, v2
	v_mov_b32_e32 v102, v2
	v_mov_b32_e32 v103, v2
	v_mov_b32_e32 v104, v2
	v_mov_b32_e32 v105, v2
	v_mov_b32_e32 v110, v2
	v_mov_b32_e32 v111, v2
	v_mov_b32_e32 v112, v2
	v_mov_b32_e32 v113, v2
	v_mov_b32_e32 v114, v2
	v_mov_b32_e32 v115, v2
	v_mov_b32_e32 v116, v2
	v_mov_b32_e32 v117, v2
	v_mov_b32_e32 v118, v2
	v_mov_b32_e32 v119, v2
	v_mov_b32_e32 v120, v2
	v_mov_b32_e32 v121, v2
	v_mov_b32_e32 v122, v2
	v_mov_b32_e32 v123, v2
	v_mov_b32_e32 v124, v2
	v_mov_b32_e32 v125, v2
	v_mov_b32_e32 v126, v2
	v_mov_b32_e32 v127, v2
	v_mov_b32_e32 v128, v2
	v_mov_b32_e32 v129, v2
	s_add_u32 s4, s44, 0x100
	s_addc_u32 s5, s45, 0
	s_add_i32 s34, 0, 0x10000
	s_cmp_eq_u32 s31, 28
	s_cselect_b32 s43, s95, s5
	s_cselect_b32 s42, s94, s4
	s_cselect_b32 s7, s27, s30
	s_cselect_b32 s6, s28, s29
	s_add_i32 s35, 0, 0x14000
	v_add_u32_e32 v142, s34, v196
	v_add_u32_e32 v158, s35, v196
	ds_read_b128 v[130:133], v142
	ds_read_b128 v[134:137], v142 offset:1024
	ds_read_b128 v[138:141], v142 offset:2048
	ds_read_b128 v[142:145], v142 offset:3072
	ds_read_b128 v[146:149], v158
	ds_read_b128 v[150:153], v158 offset:1024
	ds_read_b128 v[154:157], v158 offset:2048
	ds_read_b128 v[158:161], v158 offset:3072
	v_lshl_add_u64 v[194:195], s[44:45], 0, v[186:187]
	s_add_i32 m0, s93, 0xc000
	ds_read_b128 v[162:165], v201
	ds_read_b128 v[166:169], v201 offset:1024
	ds_read_b128 v[170:173], v201 offset:2048
	ds_read_b128 v[174:177], v201 offset:3072
	ds_read_b128 v[190:193], v201 offset:4096
	ds_read_b128 v[202:205], v201 offset:5120
	ds_read_b128 v[206:209], v201 offset:6144
	ds_read_b128 v[210:213], v201 offset:7168
	global_load_lds_dwordx4 v[194:195], off
	s_add_i32 m0, s93, 0xe000
	v_lshl_add_u64 v[194:195], s[44:45], 0, v[188:189]
	global_load_lds_dwordx4 v[194:195], off
	s_setprio 1
	s_waitcnt lgkmcnt(0)
	v_mfma_f32_16x16x32_bf16 v[126:129], v[130:133], v[162:165], v[126:129]
	v_mfma_f32_16x16x32_bf16 v[122:125], v[138:141], v[162:165], v[122:125]
	s_barrier
; #define PG8_STAGE(bufoff, gbase, voff) do { _Pragma("unroll") for (int _i = 0; _i < 2; ++_i) \
;         __builtin_amdgcn_global_load_lds((const unsigned*)((const char*)(gbase) + (voff)[_i]), (LAS unsigned*)(lds + (bufoff) + ldsw + _i * 8192), 16, 0, 0); } while (0)
; #define PG8_LDA(dst, b, h) do { _Pragma("unroll") for (int m = 0; m < 4; ++m) _Pragma("unroll") for (int k = 0; k < 2; ++k) dst[m][k] = *(const LAS bf16x8*)(lds + PG8_SA(b, h) + aoff + m * 2048 + k * 1024); } while (0)
; #define PG8_LDB(dst, b, h) do { _Pragma("unroll") for (int n = 0; n < 2; ++n) _Pragma("unroll") for (int k = 0; k < 2; ++k) dst[n][k] = *(const LAS bf16x8*)(lds + PG8_SB(b, h) + boff + n * 2048 + k * 1024); } while (0)
; #define PG8_WAIT_V(n) asm volatile("s_waitcnt vmcnt(" #n ")" ::: "memory")
; template <class Epi, int AMODE>
; __device__ __forceinline__ void gemm_phase(LAS unsigned char* lds, const Gemm g, const StaticOrder& S, const Epi& E, int stagger_us, int tid_in) {
;     ...
;         for (int t = 0; t < nt; t += 2) {
;             const bool last = (t == nt - 2);
;             const char* a1 = cA + (size_t)(t + 1) * kstep;
;             const char* a2 = last ? nA : cA + (size_t)(t + 2) * kstep; const char* b2 = last ? nB : cB + (size_t)(t + 2) * kstep;
;             const char* a3 = a2 + kstep; const char* b3 = b2 + kstep;
;             PG8_LDB(B0, 0, 0); PG8_LDB(B1, 0, 1); PG8_SCHED; PG8_LDA(At, 0, 0); PG8_STAGE(PG8_SA(1, 1), a1 + hstepA, voffA);
;             PG8_WAIT_V(8); PG8_WAIT_L(0); PG8_BAR; PG8_MMA(0, 0, At, B0); PG8_MMA(0, 1, At, B1); PG8_BAR; PG8_SCHED;
;             PG8_LDA(At, 0, 1); PG8_STAGE(PG8_SB(0, 0), b2, voffB); PG8_STAGE(PG8_SB(0, 1), b2 + hstepB, voffB); PG8_STAGE(PG8_SA(0, 0), a2, voffA);
;             PG8_WAIT_V(8); PG8_WAIT_L(0); PG8_BAR; PG8_MMA(1, 0, At, B0); PG8_MMA(1, 1, At, B1); PG8_BAR; PG8_SCHED;
;             PG8_LDB(B0, 1, 0); PG8_LDB(B1, 1, 1); PG8_SCHED; PG8_LDA(At, 1, 0); PG8_STAGE(PG8_SA(0, 1), a2 + hstepA, voffA);
;             PG8_WAIT_V(8); PG8_WAIT_L(0); PG8_BAR; PG8_MMA(0, 0, At, B0); PG8_MMA(0, 1, At, B1); PG8_BAR; PG8_SCHED;
;             PG8_LDA(At, 1, 1); PG8_STAGE(PG8_SB(1, 0), b3, voffB); PG8_STAGE(PG8_SB(1, 1), b3 + hstepB, voffB); PG8_STAGE(PG8_SA(1, 0), a3, voffA);
;             PG8_WAIT_V(8); PG8_WAIT_L(0); PG8_BAR; PG8_MMA(1, 0, At, B0); PG8_MMA(1, 1, At, B1); PG8_BAR; PG8_SCHED;
	v_mfma_f32_16x16x32_bf16 v[118:121], v[130:133], v[170:173], v[118:121]
	v_mfma_f32_16x16x32_bf16 v[114:117], v[138:141], v[170:173], v[114:117]
	v_mfma_f32_16x16x32_bf16 v[110:113], v[130:133], v[190:193], v[110:113]
	v_mfma_f32_16x16x32_bf16 v[102:105], v[138:141], v[190:193], v[102:105]
	v_mfma_f32_16x16x32_bf16 v[90:93], v[130:133], v[206:209], v[90:93]
	v_mfma_f32_16x16x32_bf16 v[82:85], v[138:141], v[206:209], v[82:85]
	v_mfma_f32_16x16x32_bf16 v[126:129], v[134:137], v[166:169], v[126:129]
	v_mfma_f32_16x16x32_bf16 v[122:125], v[142:145], v[166:169], v[122:125]
	v_mfma_f32_16x16x32_bf16 v[118:121], v[134:137], v[174:177], v[118:121]
	v_mfma_f32_16x16x32_bf16 v[114:117], v[142:145], v[174:177], v[114:117]
	v_mfma_f32_16x16x32_bf16 v[110:113], v[134:137], v[202:205], v[110:113]
	v_mfma_f32_16x16x32_bf16 v[102:105], v[142:145], v[202:205], v[102:105]
	v_mfma_f32_16x16x32_bf16 v[90:93], v[134:137], v[210:213], v[90:93]
	v_mfma_f32_16x16x32_bf16 v[82:85], v[142:145], v[210:213], v[82:85]
	v_mfma_f32_16x16x32_bf16 v[106:109], v[146:149], v[162:165], v[106:109]
	v_mfma_f32_16x16x32_bf16 v[98:101], v[154:157], v[162:165], v[98:101]
	v_mfma_f32_16x16x32_bf16 v[94:97], v[146:149], v[170:173], v[94:97]
	v_mfma_f32_16x16x32_bf16 v[86:89], v[154:157], v[170:173], v[86:89]
	v_mfma_f32_16x16x32_bf16 v[70:73], v[146:149], v[190:193], v[70:73]
	v_mfma_f32_16x16x32_bf16 v[62:65], v[154:157], v[190:193], v[62:65]
	v_mfma_f32_16x16x32_bf16 v[78:81], v[146:149], v[206:209], v[78:81]
	v_mfma_f32_16x16x32_bf16 v[66:69], v[154:157], v[206:209], v[66:69]
	v_mfma_f32_16x16x32_bf16 v[106:109], v[150:153], v[166:169], v[106:109]
	v_mfma_f32_16x16x32_bf16 v[98:101], v[158:161], v[166:169], v[98:101]
	v_mfma_f32_16x16x32_bf16 v[94:97], v[150:153], v[174:177], v[94:97]
	v_mfma_f32_16x16x32_bf16 v[86:89], v[158:161], v[174:177], v[86:89]
	v_mfma_f32_16x16x32_bf16 v[70:73], v[150:153], v[202:205], v[70:73]
	v_mfma_f32_16x16x32_bf16 v[62:65], v[158:161], v[202:205], v[62:65]
	v_mfma_f32_16x16x32_bf16 v[78:81], v[150:153], v[210:213], v[78:81]
	v_mfma_f32_16x16x32_bf16 v[66:69], v[158:161], v[210:213], v[66:69]
	s_setprio 0
	s_barrier
	s_add_i32 s34, s34, s91
	v_lshl_add_u64 v[194:195], s[6:7], 0, v[0:1]
	s_mov_b32 m0, s34
	ds_read_b128 v[162:165], v201 offset:16384
	ds_read_b128 v[166:169], v201 offset:17408
	ds_read_b128 v[170:173], v201 offset:18432
	ds_read_b128 v[174:177], v201 offset:19456
	ds_read_b128 v[190:193], v201 offset:20480
	ds_read_b128 v[202:205], v201 offset:21504
	ds_read_b128 v[206:209], v201 offset:22528
	ds_read_b128 v[210:213], v201 offset:23552
	global_load_lds_dwordx4 v[194:195], off
	s_add_i32 m0, s34, 0x2000
	s_add_u32 s44, s6, 0x80000
	v_lshl_add_u64 v[214:215], s[6:7], 0, v[182:183]
	s_addc_u32 s45, s7, 0
	s_add_i32 s34, s35, s91
	global_load_lds_dwordx4 v[214:215], off
	v_lshl_add_u64 v[216:217], s[44:45], 0, v[0:1]
	s_mov_b32 m0, s34
	v_lshl_add_u64 v[218:219], s[42:43], 0, v[180:181]
	global_load_lds_dwordx4 v[216:217], off
	s_add_i32 m0, s34, 0x2000
	v_lshl_add_u64 v[216:217], s[44:45], 0, v[182:183]
	global_load_lds_dwordx4 v[216:217], off
	s_mov_b32 m0, s93
	v_lshl_add_u64 v[216:217], s[42:43], 0, v[178:179]
	global_load_lds_dwordx4 v[216:217], off
	s_mov_b32 m0, s83
	s_nop 0
	global_load_lds_dwordx4 v[218:219], off
	s_setprio 1
	s_waitcnt lgkmcnt(0)
	v_mfma_f32_16x16x32_bf16 v[54:57], v[130:133], v[162:165], v[54:57]
	v_mfma_f32_16x16x32_bf16 v[46:49], v[138:141], v[162:165], v[46:49]
	s_barrier
	v_mfma_f32_16x16x32_bf16 v[38:41], v[130:133], v[170:173], v[38:41]
	v_mfma_f32_16x16x32_bf16 v[50:53], v[138:141], v[170:173], v[50:53]
	v_mfma_f32_16x16x32_bf16 v[18:21], v[130:133], v[190:193], v[18:21]
	v_mfma_f32_16x16x32_bf16 v[34:37], v[138:141], v[190:193], v[34:37]
	v_mfma_f32_16x16x32_bf16 v[22:25], v[130:133], v[206:209], v[22:25]
	v_mfma_f32_16x16x32_bf16 v[74:77], v[138:141], v[206:209], v[74:77]
	v_mfma_f32_16x16x32_bf16 v[54:57], v[134:137], v[166:169], v[54:57]
	v_mfma_f32_16x16x32_bf16 v[46:49], v[142:145], v[166:169], v[46:49]
	v_mfma_f32_16x16x32_bf16 v[38:41], v[134:137], v[174:177], v[38:41]
	v_mfma_f32_16x16x32_bf16 v[50:53], v[142:145], v[174:177], v[50:53]
	v_mfma_f32_16x16x32_bf16 v[18:21], v[134:137], v[202:205], v[18:21]
	v_mfma_f32_16x16x32_bf16 v[34:37], v[142:145], v[202:205], v[34:37]
	v_mfma_f32_16x16x32_bf16 v[22:25], v[134:137], v[210:213], v[22:25]
	v_mfma_f32_16x16x32_bf16 v[74:77], v[142:145], v[210:213], v[74:77]
	v_mfma_f32_16x16x32_bf16 v[58:61], v[146:149], v[162:165], v[58:61]
	v_mfma_f32_16x16x32_bf16 v[30:33], v[154:157], v[162:165], v[30:33]
	v_mfma_f32_16x16x32_bf16 v[42:45], v[146:149], v[170:173], v[42:45]
	v_mfma_f32_16x16x32_bf16 v[6:9], v[154:157], v[170:173], v[6:9]
	v_mfma_f32_16x16x32_bf16 v[26:29], v[146:149], v[190:193], v[26:29]
	v_mfma_f32_16x16x32_bf16 v[10:13], v[154:157], v[190:193], v[10:13]
	v_mfma_f32_16x16x32_bf16 v[14:17], v[146:149], v[206:209], v[14:17]
	v_mfma_f32_16x16x32_bf16 v[2:5], v[154:157], v[206:209], v[2:5]
	v_mfma_f32_16x16x32_bf16 v[58:61], v[150:153], v[166:169], v[58:61]
	v_mfma_f32_16x16x32_bf16 v[30:33], v[158:161], v[166:169], v[30:33]
	v_mfma_f32_16x16x32_bf16 v[42:45], v[150:153], v[174:177], v[42:45]
	v_mfma_f32_16x16x32_bf16 v[6:9], v[158:161], v[174:177], v[6:9]
	v_mfma_f32_16x16x32_bf16 v[26:29], v[150:153], v[202:205], v[26:29]
	v_mfma_f32_16x16x32_bf16 v[10:13], v[158:161], v[202:205], v[10:13]
	v_mfma_f32_16x16x32_bf16 v[14:17], v[150:153], v[210:213], v[14:17]
	v_mfma_f32_16x16x32_bf16 v[2:5], v[158:161], v[210:213], v[2:5]
	s_setprio 0
	s_barrier
; #define PG8_STAGE(bufoff, gbase, voff) do { _Pragma("unroll") for (int _i = 0; _i < 2; ++_i) \
;         __builtin_amdgcn_global_load_lds((const unsigned*)((const char*)(gbase) + (voff)[_i]), (LAS unsigned*)(lds + (bufoff) + ldsw + _i * 8192), 16, 0, 0); } while (0)
; #define PG8_LDA(dst, b, h) do { _Pragma("unroll") for (int m = 0; m < 4; ++m) _Pragma("unroll") for (int k = 0; k < 2; ++k) dst[m][k] = *(const LAS bf16x8*)(lds + PG8_SA(b, h) + aoff + m * 2048 + k * 1024); } while (0)
; #define PG8_LDB(dst, b, h) do { _Pragma("unroll") for (int n = 0; n < 2; ++n) _Pragma("unroll") for (int k = 0; k < 2; ++k) dst[n][k] = *(const LAS bf16x8*)(lds + PG8_SB(b, h) + boff + n * 2048 + k * 1024); } while (0)
; #define PG8_WAIT_V(n) asm volatile("s_waitcnt vmcnt(" #n ")" ::: "memory")
; template <class Epi, int AMODE>
; __device__ __forceinline__ void gemm_phase(LAS unsigned char* lds, const Gemm g, const StaticOrder& S, const Epi& E, int stagger_us, int tid_in) {
;     ...
;         for (int t = 0; t < nt; t += 2) {
;             const bool last = (t == nt - 2);
;             const char* a1 = cA + (size_t)(t + 1) * kstep;
;             const char* a2 = last ? nA : cA + (size_t)(t + 2) * kstep; const char* b2 = last ? nB : cB + (size_t)(t + 2) * kstep;
;             const char* a3 = a2 + kstep; const char* b3 = b2 + kstep;
;             PG8_LDB(B0, 0, 0); PG8_LDB(B1, 0, 1); PG8_SCHED; PG8_LDA(At, 0, 0); PG8_STAGE(PG8_SA(1, 1), a1 + hstepA, voffA);
;             PG8_WAIT_V(8); PG8_WAIT_L(0); PG8_BAR; PG8_MMA(0, 0, At, B0); PG8_MMA(0, 1, At, B1); PG8_BAR; PG8_SCHED;
;             PG8_LDA(At, 0, 1); PG8_STAGE(PG8_SB(0, 0), b2, voffB); PG8_STAGE(PG8_SB(0, 1), b2 + hstepB, voffB); PG8_STAGE(PG8_SA(0, 0), a2, voffA);
;             PG8_WAIT_V(8); PG8_WAIT_L(0); PG8_BAR; PG8_MMA(1, 0, At, B0); PG8_MMA(1, 1, At, B1); PG8_BAR; PG8_SCHED;
;             PG8_LDB(B0, 1, 0); PG8_LDB(B1, 1, 1); PG8_SCHED; PG8_LDA(At, 1, 0); PG8_STAGE(PG8_SA(0, 1), a2 + hstepA, voffA);
;             PG8_WAIT_V(8); PG8_WAIT_L(0); PG8_BAR; PG8_MMA(0, 0, At, B0); PG8_MMA(0, 1, At, B1); PG8_BAR; PG8_SCHED;
;             PG8_LDA(At, 1, 1); PG8_STAGE(PG8_SB(1, 0), b3, voffB); PG8_STAGE(PG8_SB(1, 1), b3 + hstepB, voffB); PG8_STAGE(PG8_SA(1, 0), a3, voffA);
;             PG8_WAIT_V(8); PG8_WAIT_L(0); PG8_BAR; PG8_MMA(1, 0, At, B0); PG8_MMA(1, 1, At, B1); PG8_BAR; PG8_SCHED;
	s_add_i32 s34, 0, 0x18000
	s_add_i32 s35, 0, 0x1c000
	v_add_u32_e32 v142, s34, v196
	v_add_u32_e32 v158, s35, v196
	ds_read_b128 v[130:133], v142
	ds_read_b128 v[134:137], v142 offset:1024
	ds_read_b128 v[138:141], v142 offset:2048
	ds_read_b128 v[142:145], v142 offset:3072
	ds_read_b128 v[146:149], v158
	ds_read_b128 v[150:153], v158 offset:1024
	ds_read_b128 v[154:157], v158 offset:2048
	ds_read_b128 v[158:161], v158 offset:3072
	s_add_u32 s42, s42, 0x4000
	s_addc_u32 s43, s43, 0
	s_mov_b32 m0, s79
	v_lshl_add_u64 v[220:221], s[42:43], 0, v[178:179]
	ds_read_b128 v[162:165], v201 offset:32768
	ds_read_b128 v[166:169], v201 offset:33792
	ds_read_b128 v[170:173], v201 offset:34816
	ds_read_b128 v[174:177], v201 offset:35840
	ds_read_b128 v[190:193], v201 offset:36864
	ds_read_b128 v[202:205], v201 offset:37888
	ds_read_b128 v[206:209], v201 offset:38912
	ds_read_b128 v[210:213], v201 offset:39936
	global_load_lds_dwordx4 v[220:221], off
	s_mov_b32 m0, s87
	v_lshl_add_u64 v[220:221], s[42:43], 0, v[180:181]
	global_load_lds_dwordx4 v[220:221], off
	s_setprio 1
	s_waitcnt vmcnt(8) lgkmcnt(0)
	v_mfma_f32_16x16x32_bf16 v[126:129], v[130:133], v[162:165], v[126:129]
	v_mfma_f32_16x16x32_bf16 v[122:125], v[138:141], v[162:165], v[122:125]
	s_barrier
	v_mfma_f32_16x16x32_bf16 v[118:121], v[130:133], v[170:173], v[118:121]
	v_mfma_f32_16x16x32_bf16 v[114:117], v[138:141], v[170:173], v[114:117]
	v_mfma_f32_16x16x32_bf16 v[110:113], v[130:133], v[190:193], v[110:113]
	v_mfma_f32_16x16x32_bf16 v[102:105], v[138:141], v[190:193], v[102:105]
	v_mfma_f32_16x16x32_bf16 v[90:93], v[130:133], v[206:209], v[90:93]
	v_mfma_f32_16x16x32_bf16 v[82:85], v[138:141], v[206:209], v[82:85]
	v_mfma_f32_16x16x32_bf16 v[126:129], v[134:137], v[166:169], v[126:129]
	v_mfma_f32_16x16x32_bf16 v[122:125], v[142:145], v[166:169], v[122:125]
	v_mfma_f32_16x16x32_bf16 v[118:121], v[134:137], v[174:177], v[118:121]
	v_mfma_f32_16x16x32_bf16 v[114:117], v[142:145], v[174:177], v[114:117]
	v_mfma_f32_16x16x32_bf16 v[110:113], v[134:137], v[202:205], v[110:113]
	v_mfma_f32_16x16x32_bf16 v[102:105], v[142:145], v[202:205], v[102:105]
	v_mfma_f32_16x16x32_bf16 v[90:93], v[134:137], v[210:213], v[90:93]
	v_mfma_f32_16x16x32_bf16 v[82:85], v[142:145], v[210:213], v[82:85]
	v_mfma_f32_16x16x32_bf16 v[106:109], v[146:149], v[162:165], v[106:109]
	v_mfma_f32_16x16x32_bf16 v[98:101], v[154:157], v[162:165], v[98:101]
	v_mfma_f32_16x16x32_bf16 v[94:97], v[146:149], v[170:173], v[94:97]
	v_mfma_f32_16x16x32_bf16 v[86:89], v[154:157], v[170:173], v[86:89]
	v_mfma_f32_16x16x32_bf16 v[70:73], v[146:149], v[190:193], v[70:73]
	v_mfma_f32_16x16x32_bf16 v[62:65], v[154:157], v[190:193], v[62:65]
	v_mfma_f32_16x16x32_bf16 v[78:81], v[146:149], v[206:209], v[78:81]
	v_mfma_f32_16x16x32_bf16 v[66:69], v[154:157], v[206:209], v[66:69]
	v_mfma_f32_16x16x32_bf16 v[106:109], v[150:153], v[166:169], v[106:109]
	v_mfma_f32_16x16x32_bf16 v[98:101], v[158:161], v[166:169], v[98:101]
	v_mfma_f32_16x16x32_bf16 v[94:97], v[150:153], v[174:177], v[94:97]
	v_mfma_f32_16x16x32_bf16 v[86:89], v[158:161], v[174:177], v[86:89]
	v_mfma_f32_16x16x32_bf16 v[70:73], v[150:153], v[202:205], v[70:73]
	v_mfma_f32_16x16x32_bf16 v[62:65], v[158:161], v[202:205], v[62:65]
	v_mfma_f32_16x16x32_bf16 v[78:81], v[150:153], v[210:213], v[78:81]
	v_mfma_f32_16x16x32_bf16 v[66:69], v[158:161], v[210:213], v[66:69]
	s_setprio 0
	s_barrier
	s_add_i32 s34, s34, s91
	v_lshl_add_u64 v[194:195], v[194:195], 0, s[74:75]
	s_mov_b32 m0, s34
	ds_read_b128 v[162:165], v201 offset:49152
	ds_read_b128 v[166:169], v201 offset:50176
	ds_read_b128 v[170:173], v201 offset:51200
	ds_read_b128 v[174:177], v201 offset:52224
	ds_read_b128 v[190:193], v201 offset:53248
	ds_read_b128 v[202:205], v201 offset:54272
	ds_read_b128 v[206:209], v201 offset:55296
	ds_read_b128 v[210:213], v201 offset:56320
	global_load_lds_dwordx4 v[194:195], off
	s_add_i32 m0, s34, 0x2000
	s_add_u32 s6, s6, 0x80080
	v_lshl_add_u64 v[194:195], v[214:215], 0, s[74:75]
	s_addc_u32 s7, s7, 0
	s_add_i32 s34, s35, s91
	global_load_lds_dwordx4 v[194:195], off
	s_mov_b32 m0, s34
	v_lshl_add_u64 v[194:195], s[6:7], 0, v[0:1]
	global_load_lds_dwordx4 v[194:195], off
	s_add_i32 m0, s34, 0x2000
	v_lshl_add_u64 v[194:195], s[6:7], 0, v[182:183]
	global_load_lds_dwordx4 v[194:195], off
	s_mov_b32 m0, s67
	v_lshl_add_u64 v[194:195], v[216:217], 0, s[74:75]
	global_load_lds_dwordx4 v[194:195], off
	s_mov_b32 m0, s85
	v_lshl_add_u64 v[194:195], v[218:219], 0, s[74:75]
	global_load_lds_dwordx4 v[194:195], off
	s_setprio 1
	s_waitcnt vmcnt(8) lgkmcnt(0)
	v_mfma_f32_16x16x32_bf16 v[54:57], v[130:133], v[162:165], v[54:57]
	v_mfma_f32_16x16x32_bf16 v[46:49], v[138:141], v[162:165], v[46:49]
	s_barrier
	v_mfma_f32_16x16x32_bf16 v[38:41], v[130:133], v[170:173], v[38:41]
	v_mfma_f32_16x16x32_bf16 v[50:53], v[138:141], v[170:173], v[50:53]
	v_mfma_f32_16x16x32_bf16 v[18:21], v[130:133], v[190:193], v[18:21]
	v_mfma_f32_16x16x32_bf16 v[34:37], v[138:141], v[190:193], v[34:37]
	v_mfma_f32_16x16x32_bf16 v[22:25], v[130:133], v[206:209], v[22:25]
	v_mfma_f32_16x16x32_bf16 v[74:77], v[138:141], v[206:209], v[74:77]
	v_mfma_f32_16x16x32_bf16 v[54:57], v[134:137], v[166:169], v[54:57]
	v_mfma_f32_16x16x32_bf16 v[46:49], v[142:145], v[166:169], v[46:49]
	v_mfma_f32_16x16x32_bf16 v[38:41], v[134:137], v[174:177], v[38:41]
	v_mfma_f32_16x16x32_bf16 v[50:53], v[142:145], v[174:177], v[50:53]
	v_mfma_f32_16x16x32_bf16 v[18:21], v[134:137], v[202:205], v[18:21]
	v_mfma_f32_16x16x32_bf16 v[34:37], v[142:145], v[202:205], v[34:37]
	v_mfma_f32_16x16x32_bf16 v[22:25], v[134:137], v[210:213], v[22:25]
	v_mfma_f32_16x16x32_bf16 v[74:77], v[142:145], v[210:213], v[74:77]
	v_mfma_f32_16x16x32_bf16 v[58:61], v[146:149], v[162:165], v[58:61]
	v_mfma_f32_16x16x32_bf16 v[30:33], v[154:157], v[162:165], v[30:33]
	v_mfma_f32_16x16x32_bf16 v[42:45], v[146:149], v[170:173], v[42:45]
	v_mfma_f32_16x16x32_bf16 v[6:9], v[154:157], v[170:173], v[6:9]
	v_mfma_f32_16x16x32_bf16 v[26:29], v[146:149], v[190:193], v[26:29]
	v_mfma_f32_16x16x32_bf16 v[10:13], v[154:157], v[190:193], v[10:13]
	v_mfma_f32_16x16x32_bf16 v[14:17], v[146:149], v[206:209], v[14:17]
	v_mfma_f32_16x16x32_bf16 v[2:5], v[154:157], v[206:209], v[2:5]
	v_mfma_f32_16x16x32_bf16 v[58:61], v[150:153], v[166:169], v[58:61]
	v_mfma_f32_16x16x32_bf16 v[30:33], v[158:161], v[166:169], v[30:33]
	v_mfma_f32_16x16x32_bf16 v[42:45], v[150:153], v[174:177], v[42:45]
	v_mfma_f32_16x16x32_bf16 v[6:9], v[158:161], v[174:177], v[6:9]
	v_mfma_f32_16x16x32_bf16 v[26:29], v[150:153], v[202:205], v[26:29]
	v_mfma_f32_16x16x32_bf16 v[10:13], v[158:161], v[202:205], v[10:13]
	v_mfma_f32_16x16x32_bf16 v[14:17], v[150:153], v[210:213], v[14:17]
	v_mfma_f32_16x16x32_bf16 v[2:5], v[158:161], v[210:213], v[2:5]
	s_setprio 0
	s_barrier
	s_add_i32 s31, s31, 2
	s_add_u32 s29, s29, 0x100
	s_addc_u32 s30, s30, 0
	s_cmp_gt_u32 s31, 29
	s_mov_b64 s[44:45], s[4:5]
; #define PG8_STAGE(bufoff, gbase, voff) do { _Pragma("unroll") for (int _i = 0; _i < 2; ++_i) \
;         __builtin_amdgcn_global_load_lds((const unsigned*)((const char*)(gbase) + (voff)[_i]), (LAS unsigned*)(lds + (bufoff) + ldsw + _i * 8192), 16, 0, 0); } while (0)
; #define PG8_LDA(dst, b, h) do { _Pragma("unroll") for (int m = 0; m < 4; ++m) _Pragma("unroll") for (int k = 0; k < 2; ++k) dst[m][k] = *(const LAS bf16x8*)(lds + PG8_SA(b, h) + aoff + m * 2048 + k * 1024); } while (0)
; #define PG8_LDB(dst, b, h) do { _Pragma("unroll") for (int n = 0; n < 2; ++n) _Pragma("unroll") for (int k = 0; k < 2; ++k) dst[n][k] = *(const LAS bf16x8*)(lds + PG8_SB(b, h) + boff + n * 2048 + k * 1024); } while (0)
; #define PG8_WAIT_V(n) asm volatile("s_waitcnt vmcnt(" #n ")" ::: "memory")
; template <class Epi, int AMODE>
; __device__ __forceinline__ void gemm_phase(LAS unsigned char* lds, const Gemm g, const StaticOrder& S, const Epi& E, int stagger_us, int tid_in) {
;     ...
;         for (int t = 0; t < nt; t += 2) {
;             const bool last = (t == nt - 2);
;             const char* a1 = cA + (size_t)(t + 1) * kstep;
;             const char* a2 = last ? nA : cA + (size_t)(t + 2) * kstep; const char* b2 = last ? nB : cB + (size_t)(t + 2) * kstep;
;             const char* a3 = a2 + kstep; const char* b3 = b2 + kstep;
;             PG8_LDB(B0, 0, 0); PG8_LDB(B1, 0, 1); PG8_SCHED; PG8_LDA(At, 0, 0); PG8_STAGE(PG8_SA(1, 1), a1 + hstepA, voffA);
;             PG8_WAIT_V(8); PG8_WAIT_L(0); PG8_BAR; PG8_MMA(0, 0, At, B0); PG8_MMA(0, 1, At, B1); PG8_BAR; PG8_SCHED;
;             PG8_LDA(At, 0, 1); PG8_STAGE(PG8_SB(0, 0), b2, voffB); PG8_STAGE(PG8_SB(0, 1), b2 + hstepB, voffB); PG8_STAGE(PG8_SA(0, 0), a2, voffA);
;             PG8_WAIT_V(8); PG8_WAIT_L(0); PG8_BAR; PG8_MMA(1, 0, At, B0); PG8_MMA(1, 1, At, B1); PG8_BAR; PG8_SCHED;
;             PG8_LDB(B0, 1, 0); PG8_LDB(B1, 1, 1); PG8_SCHED; PG8_LDA(At, 1, 0); PG8_STAGE(PG8_SA(0, 1), a2 + hstepA, voffA);
;             PG8_WAIT_V(8); PG8_WAIT_L(0); PG8_BAR; PG8_MMA(0, 0, At, B0); PG8_MMA(0, 1, At, B1); PG8_BAR; PG8_SCHED;
;             PG8_LDA(At, 1, 1); PG8_STAGE(PG8_SB(1, 0), b3, voffB); PG8_STAGE(PG8_SB(1, 1), b3 + hstepB, voffB); PG8_STAGE(PG8_SA(1, 0), a3, voffA);
;             PG8_WAIT_V(8); PG8_WAIT_L(0); PG8_BAR; PG8_MMA(1, 0, At, B0); PG8_MMA(1, 1, At, B1); PG8_BAR; PG8_SCHED;
.LBB0_1299:
	s_add_u32 s4, s44, 0x100
	s_addc_u32 s5, s45, 0
	s_add_i32 s34, 0, 0x10000
	s_cmp_eq_u32 s31, 28
	s_cselect_b32 s43, s95, s5
	s_cselect_b32 s42, s94, s4
	s_cselect_b32 s7, s27, s30
	s_cselect_b32 s6, s28, s29
	s_add_i32 s35, 0, 0x14000
	v_add_u32_e32 v142, s34, v196
	v_add_u32_e32 v158, s35, v196
	ds_read_b128 v[130:133], v142
	ds_read_b128 v[134:137], v142 offset:1024
	ds_read_b128 v[138:141], v142 offset:2048
	ds_read_b128 v[142:145], v142 offset:3072
	ds_read_b128 v[146:149], v158
	ds_read_b128 v[150:153], v158 offset:1024
	ds_read_b128 v[154:157], v158 offset:2048
	ds_read_b128 v[158:161], v158 offset:3072
	v_lshl_add_u64 v[194:195], s[44:45], 0, v[186:187]
	s_add_i32 m0, s93, 0xc000
	ds_read_b128 v[162:165], v201
	ds_read_b128 v[166:169], v201 offset:1024
	ds_read_b128 v[170:173], v201 offset:2048
	ds_read_b128 v[174:177], v201 offset:3072
	ds_read_b128 v[190:193], v201 offset:4096
	ds_read_b128 v[202:205], v201 offset:5120
	ds_read_b128 v[206:209], v201 offset:6144
	ds_read_b128 v[210:213], v201 offset:7168
	global_load_lds_dwordx4 v[194:195], off
	s_add_i32 m0, s93, 0xe000
	v_lshl_add_u64 v[194:195], s[44:45], 0, v[188:189]
	global_load_lds_dwordx4 v[194:195], off
	s_setprio 1
	s_waitcnt vmcnt(8) lgkmcnt(0)
	v_mfma_f32_16x16x32_bf16 v[126:129], v[130:133], v[162:165], v[126:129]
	v_mfma_f32_16x16x32_bf16 v[122:125], v[138:141], v[162:165], v[122:125]
	s_barrier
	v_mfma_f32_16x16x32_bf16 v[118:121], v[130:133], v[170:173], v[118:121]
	v_mfma_f32_16x16x32_bf16 v[114:117], v[138:141], v[170:173], v[114:117]
	v_mfma_f32_16x16x32_bf16 v[110:113], v[130:133], v[190:193], v[110:113]
	v_mfma_f32_16x16x32_bf16 v[102:105], v[138:141], v[190:193], v[102:105]
	v_mfma_f32_16x16x32_bf16 v[90:93], v[130:133], v[206:209], v[90:93]
	v_mfma_f32_16x16x32_bf16 v[82:85], v[138:141], v[206:209], v[82:85]
	v_mfma_f32_16x16x32_bf16 v[126:129], v[134:137], v[166:169], v[126:129]
	v_mfma_f32_16x16x32_bf16 v[122:125], v[142:145], v[166:169], v[122:125]
	v_mfma_f32_16x16x32_bf16 v[118:121], v[134:137], v[174:177], v[118:121]
	v_mfma_f32_16x16x32_bf16 v[114:117], v[142:145], v[174:177], v[114:117]
	v_mfma_f32_16x16x32_bf16 v[110:113], v[134:137], v[202:205], v[110:113]
	v_mfma_f32_16x16x32_bf16 v[102:105], v[142:145], v[202:205], v[102:105]
	v_mfma_f32_16x16x32_bf16 v[90:93], v[134:137], v[210:213], v[90:93]
	v_mfma_f32_16x16x32_bf16 v[82:85], v[142:145], v[210:213], v[82:85]
	v_mfma_f32_16x16x32_bf16 v[106:109], v[146:149], v[162:165], v[106:109]
	v_mfma_f32_16x16x32_bf16 v[98:101], v[154:157], v[162:165], v[98:101]
	v_mfma_f32_16x16x32_bf16 v[94:97], v[146:149], v[170:173], v[94:97]
	v_mfma_f32_16x16x32_bf16 v[86:89], v[154:157], v[170:173], v[86:89]
	v_mfma_f32_16x16x32_bf16 v[70:73], v[146:149], v[190:193], v[70:73]
	v_mfma_f32_16x16x32_bf16 v[62:65], v[154:157], v[190:193], v[62:65]
	v_mfma_f32_16x16x32_bf16 v[78:81], v[146:149], v[206:209], v[78:81]
	v_mfma_f32_16x16x32_bf16 v[66:69], v[154:157], v[206:209], v[66:69]
	v_mfma_f32_16x16x32_bf16 v[106:109], v[150:153], v[166:169], v[106:109]
	v_mfma_f32_16x16x32_bf16 v[98:101], v[158:161], v[166:169], v[98:101]
	v_mfma_f32_16x16x32_bf16 v[94:97], v[150:153], v[174:177], v[94:97]
	v_mfma_f32_16x16x32_bf16 v[86:89], v[158:161], v[174:177], v[86:89]
	v_mfma_f32_16x16x32_bf16 v[70:73], v[150:153], v[202:205], v[70:73]
	v_mfma_f32_16x16x32_bf16 v[62:65], v[158:161], v[202:205], v[62:65]
	v_mfma_f32_16x16x32_bf16 v[78:81], v[150:153], v[210:213], v[78:81]
	v_mfma_f32_16x16x32_bf16 v[66:69], v[158:161], v[210:213], v[66:69]
	s_setprio 0
	s_barrier
	s_add_i32 s34, s34, s91
	v_lshl_add_u64 v[194:195], s[6:7], 0, v[0:1]
	s_mov_b32 m0, s34
	ds_read_b128 v[162:165], v201 offset:16384
	ds_read_b128 v[166:169], v201 offset:17408
	ds_read_b128 v[170:173], v201 offset:18432
	ds_read_b128 v[174:177], v201 offset:19456
	ds_read_b128 v[190:193], v201 offset:20480
	ds_read_b128 v[202:205], v201 offset:21504
	ds_read_b128 v[206:209], v201 offset:22528
	ds_read_b128 v[210:213], v201 offset:23552
	global_load_lds_dwordx4 v[194:195], off
	s_add_i32 m0, s34, 0x2000
	s_add_u32 s44, s6, 0x80000
	v_lshl_add_u64 v[214:215], s[6:7], 0, v[182:183]
	s_addc_u32 s45, s7, 0
	s_add_i32 s34, s35, s91
	global_load_lds_dwordx4 v[214:215], off
	v_lshl_add_u64 v[216:217], s[44:45], 0, v[0:1]
	s_mov_b32 m0, s34
	v_lshl_add_u64 v[218:219], s[42:43], 0, v[180:181]
	global_load_lds_dwordx4 v[216:217], off
	s_add_i32 m0, s34, 0x2000
	v_lshl_add_u64 v[216:217], s[44:45], 0, v[182:183]
	global_load_lds_dwordx4 v[216:217], off
	s_mov_b32 m0, s93
	v_lshl_add_u64 v[216:217], s[42:43], 0, v[178:179]
	global_load_lds_dwordx4 v[216:217], off
	s_mov_b32 m0, s83
	s_nop 0
	global_load_lds_dwordx4 v[218:219], off
	s_setprio 1
	s_waitcnt vmcnt(8) lgkmcnt(0)
	v_mfma_f32_16x16x32_bf16 v[54:57], v[130:133], v[162:165], v[54:57]
	v_mfma_f32_16x16x32_bf16 v[46:49], v[138:141], v[162:165], v[46:49]
	s_barrier
; #define PG8_STAGE(bufoff, gbase, voff) do { _Pragma("unroll") for (int _i = 0; _i < 2; ++_i) \
;         __builtin_amdgcn_global_load_lds((const unsigned*)((const char*)(gbase) + (voff)[_i]), (LAS unsigned*)(lds + (bufoff) + ldsw + _i * 8192), 16, 0, 0); } while (0)
; #define PG8_LDA(dst, b, h) do { _Pragma("unroll") for (int m = 0; m < 4; ++m) _Pragma("unroll") for (int k = 0; k < 2; ++k) dst[m][k] = *(const LAS bf16x8*)(lds + PG8_SA(b, h) + aoff + m * 2048 + k * 1024); } while (0)
; #define PG8_LDB(dst, b, h) do { _Pragma("unroll") for (int n = 0; n < 2; ++n) _Pragma("unroll") for (int k = 0; k < 2; ++k) dst[n][k] = *(const LAS bf16x8*)(lds + PG8_SB(b, h) + boff + n * 2048 + k * 1024); } while (0)
; #define PG8_WAIT_V(n) asm volatile("s_waitcnt vmcnt(" #n ")" ::: "memory")
; template <class Epi, int AMODE>
; __device__ __forceinline__ void gemm_phase(LAS unsigned char* lds, const Gemm g, const StaticOrder& S, const Epi& E, int stagger_us, int tid_in) {
;     ...
;         for (int t = 0; t < nt; t += 2) {
;             const bool last = (t == nt - 2);
;             const char* a1 = cA + (size_t)(t + 1) * kstep;
;             const char* a2 = last ? nA : cA + (size_t)(t + 2) * kstep; const char* b2 = last ? nB : cB + (size_t)(t + 2) * kstep;
;             const char* a3 = a2 + kstep; const char* b3 = b2 + kstep;
;             PG8_LDB(B0, 0, 0); PG8_LDB(B1, 0, 1); PG8_SCHED; PG8_LDA(At, 0, 0); PG8_STAGE(PG8_SA(1, 1), a1 + hstepA, voffA);
;             PG8_WAIT_V(8); PG8_WAIT_L(0); PG8_BAR; PG8_MMA(0, 0, At, B0); PG8_MMA(0, 1, At, B1); PG8_BAR; PG8_SCHED;
;             PG8_LDA(At, 0, 1); PG8_STAGE(PG8_SB(0, 0), b2, voffB); PG8_STAGE(PG8_SB(0, 1), b2 + hstepB, voffB); PG8_STAGE(PG8_SA(0, 0), a2, voffA);
;             PG8_WAIT_V(8); PG8_WAIT_L(0); PG8_BAR; PG8_MMA(1, 0, At, B0); PG8_MMA(1, 1, At, B1); PG8_BAR; PG8_SCHED;
;             PG8_LDB(B0, 1, 0); PG8_LDB(B1, 1, 1); PG8_SCHED; PG8_LDA(At, 1, 0); PG8_STAGE(PG8_SA(0, 1), a2 + hstepA, voffA);
;             PG8_WAIT_V(8); PG8_WAIT_L(0); PG8_BAR; PG8_MMA(0, 0, At, B0); PG8_MMA(0, 1, At, B1); PG8_BAR; PG8_SCHED;
;             PG8_LDA(At, 1, 1); PG8_STAGE(PG8_SB(1, 0), b3, voffB); PG8_STAGE(PG8_SB(1, 1), b3 + hstepB, voffB); PG8_STAGE(PG8_SA(1, 0), a3, voffA);
;             PG8_WAIT_V(8); PG8_WAIT_L(0); PG8_BAR; PG8_MMA(1, 0, At, B0); PG8_MMA(1, 1, At, B1); PG8_BAR; PG8_SCHED;
	v_mfma_f32_16x16x32_bf16 v[38:41], v[130:133], v[170:173], v[38:41]
	v_mfma_f32_16x16x32_bf16 v[50:53], v[138:141], v[170:173], v[50:53]
	v_mfma_f32_16x16x32_bf16 v[18:21], v[130:133], v[190:193], v[18:21]
	v_mfma_f32_16x16x32_bf16 v[34:37], v[138:141], v[190:193], v[34:37]
	v_mfma_f32_16x16x32_bf16 v[22:25], v[130:133], v[206:209], v[22:25]
	v_mfma_f32_16x16x32_bf16 v[74:77], v[138:141], v[206:209], v[74:77]
	v_mfma_f32_16x16x32_bf16 v[54:57], v[134:137], v[166:169], v[54:57]
	v_mfma_f32_16x16x32_bf16 v[46:49], v[142:145], v[166:169], v[46:49]
	v_mfma_f32_16x16x32_bf16 v[38:41], v[134:137], v[174:177], v[38:41]
	v_mfma_f32_16x16x32_bf16 v[50:53], v[142:145], v[174:177], v[50:53]
	v_mfma_f32_16x16x32_bf16 v[18:21], v[134:137], v[202:205], v[18:21]
	v_mfma_f32_16x16x32_bf16 v[34:37], v[142:145], v[202:205], v[34:37]
	v_mfma_f32_16x16x32_bf16 v[22:25], v[134:137], v[210:213], v[22:25]
	v_mfma_f32_16x16x32_bf16 v[74:77], v[142:145], v[210:213], v[74:77]
	v_mfma_f32_16x16x32_bf16 v[58:61], v[146:149], v[162:165], v[58:61]
	v_mfma_f32_16x16x32_bf16 v[30:33], v[154:157], v[162:165], v[30:33]
	v_mfma_f32_16x16x32_bf16 v[42:45], v[146:149], v[170:173], v[42:45]
	v_mfma_f32_16x16x32_bf16 v[6:9], v[154:157], v[170:173], v[6:9]
	v_mfma_f32_16x16x32_bf16 v[26:29], v[146:149], v[190:193], v[26:29]
	v_mfma_f32_16x16x32_bf16 v[10:13], v[154:157], v[190:193], v[10:13]
	v_mfma_f32_16x16x32_bf16 v[14:17], v[146:149], v[206:209], v[14:17]
	v_mfma_f32_16x16x32_bf16 v[2:5], v[154:157], v[206:209], v[2:5]
	v_mfma_f32_16x16x32_bf16 v[58:61], v[150:153], v[166:169], v[58:61]
	v_mfma_f32_16x16x32_bf16 v[30:33], v[158:161], v[166:169], v[30:33]
	v_mfma_f32_16x16x32_bf16 v[42:45], v[150:153], v[174:177], v[42:45]
	v_mfma_f32_16x16x32_bf16 v[6:9], v[158:161], v[174:177], v[6:9]
	v_mfma_f32_16x16x32_bf16 v[26:29], v[150:153], v[202:205], v[26:29]
	v_mfma_f32_16x16x32_bf16 v[10:13], v[158:161], v[202:205], v[10:13]
	v_mfma_f32_16x16x32_bf16 v[14:17], v[150:153], v[210:213], v[14:17]
	v_mfma_f32_16x16x32_bf16 v[2:5], v[158:161], v[210:213], v[2:5]
	s_setprio 0
	s_barrier
	s_add_i32 s34, 0, 0x18000
	s_add_i32 s35, 0, 0x1c000
	v_add_u32_e32 v142, s34, v196
	v_add_u32_e32 v158, s35, v196
	ds_read_b128 v[130:133], v142
	ds_read_b128 v[134:137], v142 offset:1024
	ds_read_b128 v[138:141], v142 offset:2048
	ds_read_b128 v[142:145], v142 offset:3072
	ds_read_b128 v[146:149], v158
	ds_read_b128 v[150:153], v158 offset:1024
	ds_read_b128 v[154:157], v158 offset:2048
	ds_read_b128 v[158:161], v158 offset:3072
	s_add_u32 s42, s42, 0x4000
	s_addc_u32 s43, s43, 0
	s_mov_b32 m0, s79
	v_lshl_add_u64 v[220:221], s[42:43], 0, v[178:179]
	ds_read_b128 v[162:165], v201 offset:32768
	ds_read_b128 v[166:169], v201 offset:33792
	ds_read_b128 v[170:173], v201 offset:34816
	ds_read_b128 v[174:177], v201 offset:35840
	ds_read_b128 v[190:193], v201 offset:36864
	ds_read_b128 v[202:205], v201 offset:37888
	ds_read_b128 v[206:209], v201 offset:38912
	ds_read_b128 v[210:213], v201 offset:39936
	global_load_lds_dwordx4 v[220:221], off
	s_mov_b32 m0, s87
	v_lshl_add_u64 v[220:221], s[42:43], 0, v[180:181]
	global_load_lds_dwordx4 v[220:221], off
	s_setprio 1
	s_waitcnt vmcnt(8) lgkmcnt(0)
	v_mfma_f32_16x16x32_bf16 v[126:129], v[130:133], v[162:165], v[126:129]
	v_mfma_f32_16x16x32_bf16 v[122:125], v[138:141], v[162:165], v[122:125]
	s_barrier
	v_mfma_f32_16x16x32_bf16 v[118:121], v[130:133], v[170:173], v[118:121]
	v_mfma_f32_16x16x32_bf16 v[114:117], v[138:141], v[170:173], v[114:117]
	v_mfma_f32_16x16x32_bf16 v[110:113], v[130:133], v[190:193], v[110:113]
	v_mfma_f32_16x16x32_bf16 v[102:105], v[138:141], v[190:193], v[102:105]
	v_mfma_f32_16x16x32_bf16 v[90:93], v[130:133], v[206:209], v[90:93]
	v_mfma_f32_16x16x32_bf16 v[82:85], v[138:141], v[206:209], v[82:85]
	v_mfma_f32_16x16x32_bf16 v[126:129], v[134:137], v[166:169], v[126:129]
	v_mfma_f32_16x16x32_bf16 v[122:125], v[142:145], v[166:169], v[122:125]
	v_mfma_f32_16x16x32_bf16 v[118:121], v[134:137], v[174:177], v[118:121]
	v_mfma_f32_16x16x32_bf16 v[114:117], v[142:145], v[174:177], v[114:117]
	v_mfma_f32_16x16x32_bf16 v[110:113], v[134:137], v[202:205], v[110:113]
	v_mfma_f32_16x16x32_bf16 v[102:105], v[142:145], v[202:205], v[102:105]
	v_mfma_f32_16x16x32_bf16 v[90:93], v[134:137], v[210:213], v[90:93]
	v_mfma_f32_16x16x32_bf16 v[82:85], v[142:145], v[210:213], v[82:85]
	v_mfma_f32_16x16x32_bf16 v[106:109], v[146:149], v[162:165], v[106:109]
	v_mfma_f32_16x16x32_bf16 v[98:101], v[154:157], v[162:165], v[98:101]
	v_mfma_f32_16x16x32_bf16 v[94:97], v[146:149], v[170:173], v[94:97]
	v_mfma_f32_16x16x32_bf16 v[86:89], v[154:157], v[170:173], v[86:89]
	v_mfma_f32_16x16x32_bf16 v[70:73], v[146:149], v[190:193], v[70:73]
	v_mfma_f32_16x16x32_bf16 v[62:65], v[154:157], v[190:193], v[62:65]
	v_mfma_f32_16x16x32_bf16 v[78:81], v[146:149], v[206:209], v[78:81]
	v_mfma_f32_16x16x32_bf16 v[66:69], v[154:157], v[206:209], v[66:69]
	v_mfma_f32_16x16x32_bf16 v[106:109], v[150:153], v[166:169], v[106:109]
	v_mfma_f32_16x16x32_bf16 v[98:101], v[158:161], v[166:169], v[98:101]
	v_mfma_f32_16x16x32_bf16 v[94:97], v[150:153], v[174:177], v[94:97]
	v_mfma_f32_16x16x32_bf16 v[86:89], v[158:161], v[174:177], v[86:89]
	v_mfma_f32_16x16x32_bf16 v[70:73], v[150:153], v[202:205], v[70:73]
	v_mfma_f32_16x16x32_bf16 v[62:65], v[158:161], v[202:205], v[62:65]
	v_mfma_f32_16x16x32_bf16 v[78:81], v[150:153], v[210:213], v[78:81]
	v_mfma_f32_16x16x32_bf16 v[66:69], v[158:161], v[210:213], v[66:69]
	s_setprio 0
	s_barrier
; #define PG8_STAGE(bufoff, gbase, voff) do { _Pragma("unroll") for (int _i = 0; _i < 2; ++_i) \
;         __builtin_amdgcn_global_load_lds((const unsigned*)((const char*)(gbase) + (voff)[_i]), (LAS unsigned*)(lds + (bufoff) + ldsw + _i * 8192), 16, 0, 0); } while (0)
; #define PG8_LDA(dst, b, h) do { _Pragma("unroll") for (int m = 0; m < 4; ++m) _Pragma("unroll") for (int k = 0; k < 2; ++k) dst[m][k] = *(const LAS bf16x8*)(lds + PG8_SA(b, h) + aoff + m * 2048 + k * 1024); } while (0)
; #define PG8_LDB(dst, b, h) do { _Pragma("unroll") for (int n = 0; n < 2; ++n) _Pragma("unroll") for (int k = 0; k < 2; ++k) dst[n][k] = *(const LAS bf16x8*)(lds + PG8_SB(b, h) + boff + n * 2048 + k * 1024); } while (0)
; #define PG8_BAR __builtin_amdgcn_s_barrier()
; template <class Epi, int AMODE>
; __device__ __forceinline__ void gemm_phase(LAS unsigned char* lds, const Gemm g, const StaticOrder& S, const Epi& E, int stagger_us, int tid_in) {
;     ...
;         for (int t = 0; t < nt; t += 2) {
;             const bool last = (t == nt - 2);
;             const char* a1 = cA + (size_t)(t + 1) * kstep;
;             const char* a2 = last ? nA : cA + (size_t)(t + 2) * kstep; const char* b2 = last ? nB : cB + (size_t)(t + 2) * kstep;
;             const char* a3 = a2 + kstep; const char* b3 = b2 + kstep;
;             PG8_LDB(B0, 0, 0); PG8_LDB(B1, 0, 1); PG8_SCHED; PG8_LDA(At, 0, 0); PG8_STAGE(PG8_SA(1, 1), a1 + hstepA, voffA);
;             PG8_WAIT_V(8); PG8_WAIT_L(0); PG8_BAR; PG8_MMA(0, 0, At, B0); PG8_MMA(0, 1, At, B1); PG8_BAR; PG8_SCHED;
;             PG8_LDA(At, 0, 1); PG8_STAGE(PG8_SB(0, 0), b2, voffB); PG8_STAGE(PG8_SB(0, 1), b2 + hstepB, voffB); PG8_STAGE(PG8_SA(0, 0), a2, voffA);
;             PG8_WAIT_V(8); PG8_WAIT_L(0); PG8_BAR; PG8_MMA(1, 0, At, B0); PG8_MMA(1, 1, At, B1); PG8_BAR; PG8_SCHED;
;             PG8_LDB(B0, 1, 0); PG8_LDB(B1, 1, 1); PG8_SCHED; PG8_LDA(At, 1, 0); PG8_STAGE(PG8_SA(0, 1), a2 + hstepA, voffA);
;             PG8_WAIT_V(8); PG8_WAIT_L(0); PG8_BAR; PG8_MMA(0, 0, At, B0); PG8_MMA(0, 1, At, B1); PG8_BAR; PG8_SCHED;
;             PG8_LDA(At, 1, 1); PG8_STAGE(PG8_SB(1, 0), b3, voffB); PG8_STAGE(PG8_SB(1, 1), b3 + hstepB, voffB); PG8_STAGE(PG8_SA(1, 0), a3, voffA);
;             PG8_WAIT_V(8); PG8_WAIT_L(0); PG8_BAR; PG8_MMA(1, 0, At, B0); PG8_MMA(1, 1, At, B1); PG8_BAR; PG8_SCHED;
;         }
;         if (wr == 0) PG8_BAR;
	s_add_i32 s34, s34, s91
	v_lshl_add_u64 v[194:195], v[194:195], 0, s[74:75]
	s_mov_b32 m0, s34
	ds_read_b128 v[162:165], v201 offset:49152
	ds_read_b128 v[166:169], v201 offset:50176
	ds_read_b128 v[170:173], v201 offset:51200
	ds_read_b128 v[174:177], v201 offset:52224
	ds_read_b128 v[190:193], v201 offset:53248
	ds_read_b128 v[202:205], v201 offset:54272
	ds_read_b128 v[206:209], v201 offset:55296
	ds_read_b128 v[210:213], v201 offset:56320
	global_load_lds_dwordx4 v[194:195], off
	s_add_i32 m0, s34, 0x2000
	s_add_u32 s6, s6, 0x80080
	v_lshl_add_u64 v[194:195], v[214:215], 0, s[74:75]
	s_addc_u32 s7, s7, 0
	s_add_i32 s34, s35, s91
	global_load_lds_dwordx4 v[194:195], off
	s_mov_b32 m0, s34
	v_lshl_add_u64 v[194:195], s[6:7], 0, v[0:1]
	global_load_lds_dwordx4 v[194:195], off
	s_add_i32 m0, s34, 0x2000
	v_lshl_add_u64 v[194:195], s[6:7], 0, v[182:183]
	global_load_lds_dwordx4 v[194:195], off
	s_mov_b32 m0, s67
	v_lshl_add_u64 v[194:195], v[216:217], 0, s[74:75]
	global_load_lds_dwordx4 v[194:195], off
	s_mov_b32 m0, s85
	v_lshl_add_u64 v[194:195], v[218:219], 0, s[74:75]
	global_load_lds_dwordx4 v[194:195], off
	s_setprio 1
	s_waitcnt vmcnt(8) lgkmcnt(0)
	v_mfma_f32_16x16x32_bf16 v[54:57], v[130:133], v[162:165], v[54:57]
	v_mfma_f32_16x16x32_bf16 v[46:49], v[138:141], v[162:165], v[46:49]
	s_barrier
	v_mfma_f32_16x16x32_bf16 v[38:41], v[130:133], v[170:173], v[38:41]
	v_mfma_f32_16x16x32_bf16 v[50:53], v[138:141], v[170:173], v[50:53]
	v_mfma_f32_16x16x32_bf16 v[18:21], v[130:133], v[190:193], v[18:21]
	v_mfma_f32_16x16x32_bf16 v[34:37], v[138:141], v[190:193], v[34:37]
	v_mfma_f32_16x16x32_bf16 v[22:25], v[130:133], v[206:209], v[22:25]
	v_mfma_f32_16x16x32_bf16 v[74:77], v[138:141], v[206:209], v[74:77]
	v_mfma_f32_16x16x32_bf16 v[54:57], v[134:137], v[166:169], v[54:57]
	v_mfma_f32_16x16x32_bf16 v[46:49], v[142:145], v[166:169], v[46:49]
	v_mfma_f32_16x16x32_bf16 v[38:41], v[134:137], v[174:177], v[38:41]
	v_mfma_f32_16x16x32_bf16 v[50:53], v[142:145], v[174:177], v[50:53]
	v_mfma_f32_16x16x32_bf16 v[18:21], v[134:137], v[202:205], v[18:21]
	v_mfma_f32_16x16x32_bf16 v[34:37], v[142:145], v[202:205], v[34:37]
	v_mfma_f32_16x16x32_bf16 v[22:25], v[134:137], v[210:213], v[22:25]
	v_mfma_f32_16x16x32_bf16 v[74:77], v[142:145], v[210:213], v[74:77]
	v_mfma_f32_16x16x32_bf16 v[58:61], v[146:149], v[162:165], v[58:61]
	v_mfma_f32_16x16x32_bf16 v[30:33], v[154:157], v[162:165], v[30:33]
	v_mfma_f32_16x16x32_bf16 v[42:45], v[146:149], v[170:173], v[42:45]
	v_mfma_f32_16x16x32_bf16 v[6:9], v[154:157], v[170:173], v[6:9]
	v_mfma_f32_16x16x32_bf16 v[26:29], v[146:149], v[190:193], v[26:29]
	v_mfma_f32_16x16x32_bf16 v[10:13], v[154:157], v[190:193], v[10:13]
	v_mfma_f32_16x16x32_bf16 v[14:17], v[146:149], v[206:209], v[14:17]
	v_mfma_f32_16x16x32_bf16 v[2:5], v[154:157], v[206:209], v[2:5]
	v_mfma_f32_16x16x32_bf16 v[58:61], v[150:153], v[166:169], v[58:61]
	v_mfma_f32_16x16x32_bf16 v[30:33], v[158:161], v[166:169], v[30:33]
	v_mfma_f32_16x16x32_bf16 v[42:45], v[150:153], v[174:177], v[42:45]
	v_mfma_f32_16x16x32_bf16 v[6:9], v[158:161], v[174:177], v[6:9]
	v_mfma_f32_16x16x32_bf16 v[26:29], v[150:153], v[202:205], v[26:29]
	v_mfma_f32_16x16x32_bf16 v[10:13], v[158:161], v[202:205], v[10:13]
	v_mfma_f32_16x16x32_bf16 v[14:17], v[150:153], v[210:213], v[14:17]
	v_mfma_f32_16x16x32_bf16 v[2:5], v[158:161], v[210:213], v[2:5]
	s_setprio 0
	s_barrier
	s_add_i32 s31, s31, 2
	s_add_u32 s29, s29, 0x100
	s_addc_u32 s30, s30, 0
	s_cmp_gt_u32 s31, 29
	s_mov_b64 s[44:45], s[4:5]
	s_cbranch_scc0 .LBB0_1299
	s_and_b64 vcc, exec, s[48:49]
	s_cbranch_vccz .LBB0_1302
	s_barrier

; #define PG8_STAGE(bufoff, gbase, voff) do { _Pragma("unroll") for (int _i = 0; _i < 2; ++_i) \
;         __builtin_amdgcn_global_load_lds((const unsigned*)((const char*)(gbase) + (voff)[_i]), (LAS unsigned*)(lds + (bufoff) + ldsw + _i * 8192), 16, 0, 0); } while (0)
; #define PG8_LDA(dst, b, h) do { _Pragma("unroll") for (int m = 0; m < 4; ++m) _Pragma("unroll") for (int k = 0; k < 2; ++k) dst[m][k] = *(const LAS bf16x8*)(lds + PG8_SA(b, h) + aoff + m * 2048 + k * 1024); } while (0)
; #define PG8_LDB(dst, b, h) do { _Pragma("unroll") for (int n = 0; n < 2; ++n) _Pragma("unroll") for (int k = 0; k < 2; ++k) dst[n][k] = *(const LAS bf16x8*)(lds + PG8_SB(b, h) + boff + n * 2048 + k * 1024); } while (0)
; #define PG8_WAIT_V(n) asm volatile("s_waitcnt vmcnt(" #n ")" ::: "memory")
; template <class Epi, int AMODE>
; __device__ __forceinline__ void gemm_phase(LAS unsigned char* lds, const Gemm g, const StaticOrder& S, const Epi& E, int stagger_us, int tid_in) {
;     ...
;         for (int t = 0; t < nt; t += 2) {
;             const bool last = (t == nt - 2);
;             const char* a1 = cA + (size_t)(t + 1) * kstep;
;             const char* a2 = last ? nA : cA + (size_t)(t + 2) * kstep; const char* b2 = last ? nB : cB + (size_t)(t + 2) * kstep;
;             const char* a3 = a2 + kstep; const char* b3 = b2 + kstep;
;             PG8_LDB(B0, 0, 0); PG8_LDB(B1, 0, 1); PG8_SCHED; PG8_LDA(At, 0, 0); PG8_STAGE(PG8_SA(1, 1), a1 + hstepA, voffA);
;             PG8_WAIT_V(8); PG8_WAIT_L(0); PG8_BAR; PG8_MMA(0, 0, At, B0); PG8_MMA(0, 1, At, B1); PG8_BAR; PG8_SCHED;
;             PG8_LDA(At, 0, 1); PG8_STAGE(PG8_SB(0, 0), b2, voffB); PG8_STAGE(PG8_SB(0, 1), b2 + hstepB, voffB); PG8_STAGE(PG8_SA(0, 0), a2, voffA);
;             PG8_WAIT_V(8); PG8_WAIT_L(0); PG8_BAR; PG8_MMA(1, 0, At, B0); PG8_MMA(1, 1, At, B1); PG8_BAR; PG8_SCHED;
;             PG8_LDB(B0, 1, 0); PG8_LDB(B1, 1, 1); PG8_SCHED; PG8_LDA(At, 1, 0); PG8_STAGE(PG8_SA(0, 1), a2 + hstepA, voffA);
;             PG8_WAIT_V(8); PG8_WAIT_L(0); PG8_BAR; PG8_MMA(0, 0, At, B0); PG8_MMA(0, 1, At, B1); PG8_BAR; PG8_SCHED;
;             PG8_LDA(At, 1, 1); PG8_STAGE(PG8_SB(1, 0), b3, voffB); PG8_STAGE(PG8_SB(1, 1), b3 + hstepB, voffB); PG8_STAGE(PG8_SA(1, 0), a3, voffA);
;             PG8_WAIT_V(8); PG8_WAIT_L(0); PG8_BAR; PG8_MMA(1, 0, At, B0); PG8_MMA(1, 1, At, B1); PG8_BAR; PG8_SCHED;
.LBB0_1476:
	s_add_u32 s4, s54, 0x100
	s_addc_u32 s5, s55, 0
	s_add_i32 s30, 0, 0x10000
	s_cmpk_eq_i32 s29, 0x52
	s_cselect_b32 s57, s41, s5
	s_cselect_b32 s56, s40, s4
	s_cselect_b32 s7, s53, s28
	s_cselect_b32 s6, s52, s27
	s_add_i32 s34, 0, 0x14000
	v_add_u32_e32 v102, s30, v162
	v_add_u32_e32 v165, s34, v162
	ds_read_b128 v[66:69], v102
	ds_read_b128 v[70:73], v102 offset:1024
	ds_read_b128 v[74:77], v102 offset:2048
	ds_read_b128 v[102:105], v102 offset:3072
	ds_read_b128 v[152:155], v165
	ds_read_b128 v[156:159], v165 offset:1024
	ds_read_b128 v[166:169], v165 offset:2048
	ds_read_b128 v[170:173], v165 offset:3072
	v_lshl_add_u64 v[206:207], s[54:55], 0, v[148:149]
	s_add_i32 m0, s13, 0xc000
	ds_read_b128 v[174:177], v164
	ds_read_b128 v[178:181], v164 offset:1024
	ds_read_b128 v[182:185], v164 offset:2048
	ds_read_b128 v[186:189], v164 offset:3072
	ds_read_b128 v[190:193], v164 offset:4096
	ds_read_b128 v[194:197], v164 offset:5120
	ds_read_b128 v[198:201], v164 offset:6144
	ds_read_b128 v[202:205], v164 offset:7168
	global_load_lds_dwordx4 v[206:207], off
	s_add_i32 m0, s13, 0xe000
	v_lshl_add_u64 v[206:207], s[54:55], 0, v[150:151]
	global_load_lds_dwordx4 v[206:207], off
	s_setprio 1
	s_waitcnt vmcnt(8) lgkmcnt(0)
	v_mfma_f32_16x16x32_bf16 v[142:145], v[66:69], v[174:177], v[142:145]
	v_mfma_f32_16x16x32_bf16 v[138:141], v[74:77], v[174:177], v[138:141]
	s_barrier
	v_mfma_f32_16x16x32_bf16 v[134:137], v[66:69], v[182:185], v[134:137]
	v_mfma_f32_16x16x32_bf16 v[130:133], v[74:77], v[182:185], v[130:133]
	v_mfma_f32_16x16x32_bf16 v[110:113], v[66:69], v[190:193], v[110:113]
	v_mfma_f32_16x16x32_bf16 v[106:109], v[74:77], v[190:193], v[106:109]
	v_mfma_f32_16x16x32_bf16 v[98:101], v[66:69], v[198:201], v[98:101]
	v_mfma_f32_16x16x32_bf16 v[94:97], v[74:77], v[198:201], v[94:97]
	v_mfma_f32_16x16x32_bf16 v[142:145], v[70:73], v[178:181], v[142:145]
	v_mfma_f32_16x16x32_bf16 v[138:141], v[102:105], v[178:181], v[138:141]
	v_mfma_f32_16x16x32_bf16 v[134:137], v[70:73], v[186:189], v[134:137]
	v_mfma_f32_16x16x32_bf16 v[130:133], v[102:105], v[186:189], v[130:133]
	v_mfma_f32_16x16x32_bf16 v[110:113], v[70:73], v[194:197], v[110:113]
	v_mfma_f32_16x16x32_bf16 v[106:109], v[102:105], v[194:197], v[106:109]
	v_mfma_f32_16x16x32_bf16 v[98:101], v[70:73], v[202:205], v[98:101]
	v_mfma_f32_16x16x32_bf16 v[94:97], v[102:105], v[202:205], v[94:97]
	v_mfma_f32_16x16x32_bf16 v[126:129], v[152:155], v[174:177], v[126:129]
	v_mfma_f32_16x16x32_bf16 v[122:125], v[166:169], v[174:177], v[122:125]
	v_mfma_f32_16x16x32_bf16 v[118:121], v[152:155], v[182:185], v[118:121]
	v_mfma_f32_16x16x32_bf16 v[114:117], v[166:169], v[182:185], v[114:117]
	v_mfma_f32_16x16x32_bf16 v[90:93], v[152:155], v[190:193], v[90:93]
	v_mfma_f32_16x16x32_bf16 v[86:89], v[166:169], v[190:193], v[86:89]
	v_mfma_f32_16x16x32_bf16 v[82:85], v[152:155], v[198:201], v[82:85]
	v_mfma_f32_16x16x32_bf16 v[78:81], v[166:169], v[198:201], v[78:81]
	v_mfma_f32_16x16x32_bf16 v[126:129], v[156:159], v[178:181], v[126:129]
	v_mfma_f32_16x16x32_bf16 v[122:125], v[170:173], v[178:181], v[122:125]
	v_mfma_f32_16x16x32_bf16 v[118:121], v[156:159], v[186:189], v[118:121]
	v_mfma_f32_16x16x32_bf16 v[114:117], v[170:173], v[186:189], v[114:117]
	v_mfma_f32_16x16x32_bf16 v[90:93], v[156:159], v[194:197], v[90:93]
	v_mfma_f32_16x16x32_bf16 v[86:89], v[170:173], v[194:197], v[86:89]
	v_mfma_f32_16x16x32_bf16 v[82:85], v[156:159], v[202:205], v[82:85]
	v_mfma_f32_16x16x32_bf16 v[78:81], v[170:173], v[202:205], v[78:81]
	s_setprio 0
	s_barrier
	s_add_i32 s30, s30, s12
	v_lshl_add_u64 v[206:207], s[6:7], 0, v[0:1]
	s_mov_b32 m0, s30
	ds_read_b128 v[174:177], v164 offset:16384
	ds_read_b128 v[178:181], v164 offset:17408
	ds_read_b128 v[182:185], v164 offset:18432
	ds_read_b128 v[186:189], v164 offset:19456
	ds_read_b128 v[190:193], v164 offset:20480
	ds_read_b128 v[194:197], v164 offset:21504
	ds_read_b128 v[198:201], v164 offset:22528
	ds_read_b128 v[202:205], v164 offset:23552
	global_load_lds_dwordx4 v[206:207], off
	s_add_i32 m0, s30, 0x2000
	s_add_u32 s30, s6, 0x158000
	v_lshl_add_u64 v[208:209], s[6:7], 0, v[146:147]
	s_addc_u32 s31, s7, 0
	s_add_i32 s34, s34, s12
	global_load_lds_dwordx4 v[208:209], off
	v_lshl_add_u64 v[210:211], s[30:31], 0, v[0:1]
	s_mov_b32 m0, s34
	v_lshl_add_u64 v[212:213], s[56:57], 0, v[146:147]
	global_load_lds_dwordx4 v[210:211], off
	s_add_i32 m0, s34, 0x2000
	v_lshl_add_u64 v[210:211], s[30:31], 0, v[146:147]
	global_load_lds_dwordx4 v[210:211], off
	s_mov_b32 m0, s13
	v_lshl_add_u64 v[210:211], s[56:57], 0, v[0:1]
	global_load_lds_dwordx4 v[210:211], off
	s_mov_b32 m0, s24
	s_nop 0
	global_load_lds_dwordx4 v[212:213], off
	s_setprio 1
	s_waitcnt vmcnt(8) lgkmcnt(0)
	v_mfma_f32_16x16x32_bf16 v[62:65], v[66:69], v[174:177], v[62:65]
	v_mfma_f32_16x16x32_bf16 v[58:61], v[74:77], v[174:177], v[58:61]
	s_barrier
; #define PG8_STAGE(bufoff, gbase, voff) do { _Pragma("unroll") for (int _i = 0; _i < 2; ++_i) \
;         __builtin_amdgcn_global_load_lds((const unsigned*)((const char*)(gbase) + (voff)[_i]), (LAS unsigned*)(lds + (bufoff) + ldsw + _i * 8192), 16, 0, 0); } while (0)
; #define PG8_LDA(dst, b, h) do { _Pragma("unroll") for (int m = 0; m < 4; ++m) _Pragma("unroll") for (int k = 0; k < 2; ++k) dst[m][k] = *(const LAS bf16x8*)(lds + PG8_SA(b, h) + aoff + m * 2048 + k * 1024); } while (0)
; #define PG8_LDB(dst, b, h) do { _Pragma("unroll") for (int n = 0; n < 2; ++n) _Pragma("unroll") for (int k = 0; k < 2; ++k) dst[n][k] = *(const LAS bf16x8*)(lds + PG8_SB(b, h) + boff + n * 2048 + k * 1024); } while (0)
; #define PG8_WAIT_V(n) asm volatile("s_waitcnt vmcnt(" #n ")" ::: "memory")
; template <class Epi, int AMODE>
; __device__ __forceinline__ void gemm_phase(LAS unsigned char* lds, const Gemm g, const StaticOrder& S, const Epi& E, int stagger_us, int tid_in) {
;     ...
;         for (int t = 0; t < nt; t += 2) {
;             const bool last = (t == nt - 2);
;             const char* a1 = cA + (size_t)(t + 1) * kstep;
;             const char* a2 = last ? nA : cA + (size_t)(t + 2) * kstep; const char* b2 = last ? nB : cB + (size_t)(t + 2) * kstep;
;             const char* a3 = a2 + kstep; const char* b3 = b2 + kstep;
;             PG8_LDB(B0, 0, 0); PG8_LDB(B1, 0, 1); PG8_SCHED; PG8_LDA(At, 0, 0); PG8_STAGE(PG8_SA(1, 1), a1 + hstepA, voffA);
;             PG8_WAIT_V(8); PG8_WAIT_L(0); PG8_BAR; PG8_MMA(0, 0, At, B0); PG8_MMA(0, 1, At, B1); PG8_BAR; PG8_SCHED;
;             PG8_LDA(At, 0, 1); PG8_STAGE(PG8_SB(0, 0), b2, voffB); PG8_STAGE(PG8_SB(0, 1), b2 + hstepB, voffB); PG8_STAGE(PG8_SA(0, 0), a2, voffA);
;             PG8_WAIT_V(8); PG8_WAIT_L(0); PG8_BAR; PG8_MMA(1, 0, At, B0); PG8_MMA(1, 1, At, B1); PG8_BAR; PG8_SCHED;
;             PG8_LDB(B0, 1, 0); PG8_LDB(B1, 1, 1); PG8_SCHED; PG8_LDA(At, 1, 0); PG8_STAGE(PG8_SA(0, 1), a2 + hstepA, voffA);
;             PG8_WAIT_V(8); PG8_WAIT_L(0); PG8_BAR; PG8_MMA(0, 0, At, B0); PG8_MMA(0, 1, At, B1); PG8_BAR; PG8_SCHED;
;             PG8_LDA(At, 1, 1); PG8_STAGE(PG8_SB(1, 0), b3, voffB); PG8_STAGE(PG8_SB(1, 1), b3 + hstepB, voffB); PG8_STAGE(PG8_SA(1, 0), a3, voffA);
;             PG8_WAIT_V(8); PG8_WAIT_L(0); PG8_BAR; PG8_MMA(1, 0, At, B0); PG8_MMA(1, 1, At, B1); PG8_BAR; PG8_SCHED;
	v_mfma_f32_16x16x32_bf16 v[54:57], v[66:69], v[182:185], v[54:57]
	v_mfma_f32_16x16x32_bf16 v[50:53], v[74:77], v[182:185], v[50:53]
	v_mfma_f32_16x16x32_bf16 v[30:33], v[66:69], v[190:193], v[30:33]
	v_mfma_f32_16x16x32_bf16 v[26:29], v[74:77], v[190:193], v[26:29]
	v_mfma_f32_16x16x32_bf16 v[22:25], v[66:69], v[198:201], v[22:25]
	v_mfma_f32_16x16x32_bf16 v[10:13], v[74:77], v[198:201], v[10:13]
	v_mfma_f32_16x16x32_bf16 v[62:65], v[70:73], v[178:181], v[62:65]
	v_mfma_f32_16x16x32_bf16 v[58:61], v[102:105], v[178:181], v[58:61]
	v_mfma_f32_16x16x32_bf16 v[54:57], v[70:73], v[186:189], v[54:57]
	v_mfma_f32_16x16x32_bf16 v[50:53], v[102:105], v[186:189], v[50:53]
	v_mfma_f32_16x16x32_bf16 v[30:33], v[70:73], v[194:197], v[30:33]
	v_mfma_f32_16x16x32_bf16 v[26:29], v[102:105], v[194:197], v[26:29]
	v_mfma_f32_16x16x32_bf16 v[22:25], v[70:73], v[202:205], v[22:25]
	v_mfma_f32_16x16x32_bf16 v[10:13], v[102:105], v[202:205], v[10:13]
	v_mfma_f32_16x16x32_bf16 v[46:49], v[152:155], v[174:177], v[46:49]
	v_mfma_f32_16x16x32_bf16 v[42:45], v[166:169], v[174:177], v[42:45]
	v_mfma_f32_16x16x32_bf16 v[38:41], v[152:155], v[182:185], v[38:41]
	v_mfma_f32_16x16x32_bf16 v[34:37], v[166:169], v[182:185], v[34:37]
	v_mfma_f32_16x16x32_bf16 v[18:21], v[152:155], v[190:193], v[18:21]
	v_mfma_f32_16x16x32_bf16 v[14:17], v[166:169], v[190:193], v[14:17]
	v_mfma_f32_16x16x32_bf16 v[6:9], v[152:155], v[198:201], v[6:9]
	v_mfma_f32_16x16x32_bf16 v[2:5], v[166:169], v[198:201], v[2:5]
	v_mfma_f32_16x16x32_bf16 v[46:49], v[156:159], v[178:181], v[46:49]
	v_mfma_f32_16x16x32_bf16 v[42:45], v[170:173], v[178:181], v[42:45]
	v_mfma_f32_16x16x32_bf16 v[38:41], v[156:159], v[186:189], v[38:41]
	v_mfma_f32_16x16x32_bf16 v[34:37], v[170:173], v[186:189], v[34:37]
	v_mfma_f32_16x16x32_bf16 v[18:21], v[156:159], v[194:197], v[18:21]
	v_mfma_f32_16x16x32_bf16 v[14:17], v[170:173], v[194:197], v[14:17]
	v_mfma_f32_16x16x32_bf16 v[6:9], v[156:159], v[202:205], v[6:9]
	v_mfma_f32_16x16x32_bf16 v[2:5], v[170:173], v[202:205], v[2:5]
	s_setprio 0
	s_barrier
	s_add_i32 s34, 0, 0x18000
	s_add_i32 s35, 0, 0x1c000
	v_add_u32_e32 v102, s34, v162
	v_add_u32_e32 v165, s35, v162
	ds_read_b128 v[66:69], v102
	ds_read_b128 v[70:73], v102 offset:1024
	ds_read_b128 v[74:77], v102 offset:2048
	ds_read_b128 v[102:105], v102 offset:3072
	ds_read_b128 v[152:155], v165
	ds_read_b128 v[156:159], v165 offset:1024
	ds_read_b128 v[166:169], v165 offset:2048
	ds_read_b128 v[170:173], v165 offset:3072
	s_add_u32 s30, s56, 0x158000
	s_addc_u32 s31, s57, 0
	s_mov_b32 m0, s25
	v_lshl_add_u64 v[214:215], s[30:31], 0, v[0:1]
	ds_read_b128 v[174:177], v164 offset:32768
	ds_read_b128 v[178:181], v164 offset:33792
	ds_read_b128 v[182:185], v164 offset:34816
	ds_read_b128 v[186:189], v164 offset:35840
	ds_read_b128 v[190:193], v164 offset:36864
	ds_read_b128 v[194:197], v164 offset:37888
	ds_read_b128 v[198:201], v164 offset:38912
	ds_read_b128 v[202:205], v164 offset:39936
	global_load_lds_dwordx4 v[214:215], off
	s_mov_b32 m0, s66
	v_lshl_add_u64 v[214:215], s[30:31], 0, v[146:147]
	global_load_lds_dwordx4 v[214:215], off
	s_setprio 1
	s_waitcnt vmcnt(8) lgkmcnt(0)
	v_mfma_f32_16x16x32_bf16 v[142:145], v[66:69], v[174:177], v[142:145]
	v_mfma_f32_16x16x32_bf16 v[138:141], v[74:77], v[174:177], v[138:141]
	s_barrier
	v_mfma_f32_16x16x32_bf16 v[134:137], v[66:69], v[182:185], v[134:137]
	v_mfma_f32_16x16x32_bf16 v[130:133], v[74:77], v[182:185], v[130:133]
	v_mfma_f32_16x16x32_bf16 v[110:113], v[66:69], v[190:193], v[110:113]
	v_mfma_f32_16x16x32_bf16 v[106:109], v[74:77], v[190:193], v[106:109]
	v_mfma_f32_16x16x32_bf16 v[98:101], v[66:69], v[198:201], v[98:101]
	v_mfma_f32_16x16x32_bf16 v[94:97], v[74:77], v[198:201], v[94:97]
	v_mfma_f32_16x16x32_bf16 v[142:145], v[70:73], v[178:181], v[142:145]
	v_mfma_f32_16x16x32_bf16 v[138:141], v[102:105], v[178:181], v[138:141]
	v_mfma_f32_16x16x32_bf16 v[134:137], v[70:73], v[186:189], v[134:137]
	v_mfma_f32_16x16x32_bf16 v[130:133], v[102:105], v[186:189], v[130:133]
	v_mfma_f32_16x16x32_bf16 v[110:113], v[70:73], v[194:197], v[110:113]
	v_mfma_f32_16x16x32_bf16 v[106:109], v[102:105], v[194:197], v[106:109]
	v_mfma_f32_16x16x32_bf16 v[98:101], v[70:73], v[202:205], v[98:101]
	v_mfma_f32_16x16x32_bf16 v[94:97], v[102:105], v[202:205], v[94:97]
	v_mfma_f32_16x16x32_bf16 v[126:129], v[152:155], v[174:177], v[126:129]
	v_mfma_f32_16x16x32_bf16 v[122:125], v[166:169], v[174:177], v[122:125]
	v_mfma_f32_16x16x32_bf16 v[118:121], v[152:155], v[182:185], v[118:121]
	v_mfma_f32_16x16x32_bf16 v[114:117], v[166:169], v[182:185], v[114:117]
	v_mfma_f32_16x16x32_bf16 v[90:93], v[152:155], v[190:193], v[90:93]
	v_mfma_f32_16x16x32_bf16 v[86:89], v[166:169], v[190:193], v[86:89]
	v_mfma_f32_16x16x32_bf16 v[82:85], v[152:155], v[198:201], v[82:85]
	v_mfma_f32_16x16x32_bf16 v[78:81], v[166:169], v[198:201], v[78:81]
	v_mfma_f32_16x16x32_bf16 v[126:129], v[156:159], v[178:181], v[126:129]
	v_mfma_f32_16x16x32_bf16 v[122:125], v[170:173], v[178:181], v[122:125]
	v_mfma_f32_16x16x32_bf16 v[118:121], v[156:159], v[186:189], v[118:121]
	v_mfma_f32_16x16x32_bf16 v[114:117], v[170:173], v[186:189], v[114:117]
	v_mfma_f32_16x16x32_bf16 v[90:93], v[156:159], v[194:197], v[90:93]
	v_mfma_f32_16x16x32_bf16 v[86:89], v[170:173], v[194:197], v[86:89]
	v_mfma_f32_16x16x32_bf16 v[82:85], v[156:159], v[202:205], v[82:85]
	v_mfma_f32_16x16x32_bf16 v[78:81], v[170:173], v[202:205], v[78:81]
	s_setprio 0
	s_barrier
; #define PG8_STAGE(bufoff, gbase, voff) do { _Pragma("unroll") for (int _i = 0; _i < 2; ++_i) \
;         __builtin_amdgcn_global_load_lds((const unsigned*)((const char*)(gbase) + (voff)[_i]), (LAS unsigned*)(lds + (bufoff) + ldsw + _i * 8192), 16, 0, 0); } while (0)
; #define PG8_LDA(dst, b, h) do { _Pragma("unroll") for (int m = 0; m < 4; ++m) _Pragma("unroll") for (int k = 0; k < 2; ++k) dst[m][k] = *(const LAS bf16x8*)(lds + PG8_SA(b, h) + aoff + m * 2048 + k * 1024); } while (0)
; #define PG8_LDB(dst, b, h) do { _Pragma("unroll") for (int n = 0; n < 2; ++n) _Pragma("unroll") for (int k = 0; k < 2; ++k) dst[n][k] = *(const LAS bf16x8*)(lds + PG8_SB(b, h) + boff + n * 2048 + k * 1024); } while (0)
; #define PG8_BAR __builtin_amdgcn_s_barrier()
; template <class Epi, int AMODE>
; __device__ __forceinline__ void gemm_phase(LAS unsigned char* lds, const Gemm g, const StaticOrder& S, const Epi& E, int stagger_us, int tid_in) {
;     ...
;         for (int t = 0; t < nt; t += 2) {
;             const bool last = (t == nt - 2);
;             const char* a1 = cA + (size_t)(t + 1) * kstep;
;             const char* a2 = last ? nA : cA + (size_t)(t + 2) * kstep; const char* b2 = last ? nB : cB + (size_t)(t + 2) * kstep;
;             const char* a3 = a2 + kstep; const char* b3 = b2 + kstep;
;             PG8_LDB(B0, 0, 0); PG8_LDB(B1, 0, 1); PG8_SCHED; PG8_LDA(At, 0, 0); PG8_STAGE(PG8_SA(1, 1), a1 + hstepA, voffA);
;             PG8_WAIT_V(8); PG8_WAIT_L(0); PG8_BAR; PG8_MMA(0, 0, At, B0); PG8_MMA(0, 1, At, B1); PG8_BAR; PG8_SCHED;
;             PG8_LDA(At, 0, 1); PG8_STAGE(PG8_SB(0, 0), b2, voffB); PG8_STAGE(PG8_SB(0, 1), b2 + hstepB, voffB); PG8_STAGE(PG8_SA(0, 0), a2, voffA);
;             PG8_WAIT_V(8); PG8_WAIT_L(0); PG8_BAR; PG8_MMA(1, 0, At, B0); PG8_MMA(1, 1, At, B1); PG8_BAR; PG8_SCHED;
;             PG8_LDB(B0, 1, 0); PG8_LDB(B1, 1, 1); PG8_SCHED; PG8_LDA(At, 1, 0); PG8_STAGE(PG8_SA(0, 1), a2 + hstepA, voffA);
;             PG8_WAIT_V(8); PG8_WAIT_L(0); PG8_BAR; PG8_MMA(0, 0, At, B0); PG8_MMA(0, 1, At, B1); PG8_BAR; PG8_SCHED;
;             PG8_LDA(At, 1, 1); PG8_STAGE(PG8_SB(1, 0), b3, voffB); PG8_STAGE(PG8_SB(1, 1), b3 + hstepB, voffB); PG8_STAGE(PG8_SA(1, 0), a3, voffA);
;             PG8_WAIT_V(8); PG8_WAIT_L(0); PG8_BAR; PG8_MMA(1, 0, At, B0); PG8_MMA(1, 1, At, B1); PG8_BAR; PG8_SCHED;
;         }
;         if (wr == 0) PG8_BAR;
	s_add_i32 s30, s34, s12
	v_lshl_add_u64 v[206:207], v[206:207], 0, s[74:75]
	s_mov_b32 m0, s30
	ds_read_b128 v[174:177], v164 offset:49152
	ds_read_b128 v[178:181], v164 offset:50176
	ds_read_b128 v[182:185], v164 offset:51200
	ds_read_b128 v[186:189], v164 offset:52224
	ds_read_b128 v[190:193], v164 offset:53248
	ds_read_b128 v[194:197], v164 offset:54272
	ds_read_b128 v[198:201], v164 offset:55296
	ds_read_b128 v[202:205], v164 offset:56320
	global_load_lds_dwordx4 v[206:207], off
	s_add_i32 m0, s30, 0x2000
	s_add_u32 s6, s6, 0x158080
	v_lshl_add_u64 v[206:207], v[208:209], 0, s[74:75]
	s_addc_u32 s7, s7, 0
	s_add_i32 s30, s35, s12
	global_load_lds_dwordx4 v[206:207], off
	s_mov_b32 m0, s30
	v_lshl_add_u64 v[206:207], s[6:7], 0, v[0:1]
	global_load_lds_dwordx4 v[206:207], off
	s_add_i32 m0, s30, 0x2000
	v_lshl_add_u64 v[206:207], s[6:7], 0, v[146:147]
	global_load_lds_dwordx4 v[206:207], off
	s_mov_b32 m0, s67
	v_lshl_add_u64 v[206:207], v[210:211], 0, s[74:75]
	global_load_lds_dwordx4 v[206:207], off
	s_mov_b32 m0, s69
	v_lshl_add_u64 v[206:207], v[212:213], 0, s[74:75]
	global_load_lds_dwordx4 v[206:207], off
	s_setprio 1
	s_waitcnt vmcnt(8) lgkmcnt(0)
	v_mfma_f32_16x16x32_bf16 v[62:65], v[66:69], v[174:177], v[62:65]
	v_mfma_f32_16x16x32_bf16 v[58:61], v[74:77], v[174:177], v[58:61]
	s_barrier
	v_mfma_f32_16x16x32_bf16 v[54:57], v[66:69], v[182:185], v[54:57]
	v_mfma_f32_16x16x32_bf16 v[50:53], v[74:77], v[182:185], v[50:53]
	v_mfma_f32_16x16x32_bf16 v[30:33], v[66:69], v[190:193], v[30:33]
	v_mfma_f32_16x16x32_bf16 v[26:29], v[74:77], v[190:193], v[26:29]
	v_mfma_f32_16x16x32_bf16 v[22:25], v[66:69], v[198:201], v[22:25]
	v_mfma_f32_16x16x32_bf16 v[10:13], v[74:77], v[198:201], v[10:13]
	v_mfma_f32_16x16x32_bf16 v[62:65], v[70:73], v[178:181], v[62:65]
	v_mfma_f32_16x16x32_bf16 v[58:61], v[102:105], v[178:181], v[58:61]
	v_mfma_f32_16x16x32_bf16 v[54:57], v[70:73], v[186:189], v[54:57]
	v_mfma_f32_16x16x32_bf16 v[50:53], v[102:105], v[186:189], v[50:53]
	v_mfma_f32_16x16x32_bf16 v[30:33], v[70:73], v[194:197], v[30:33]
	v_mfma_f32_16x16x32_bf16 v[26:29], v[102:105], v[194:197], v[26:29]
	v_mfma_f32_16x16x32_bf16 v[22:25], v[70:73], v[202:205], v[22:25]
	v_mfma_f32_16x16x32_bf16 v[10:13], v[102:105], v[202:205], v[10:13]
	v_mfma_f32_16x16x32_bf16 v[46:49], v[152:155], v[174:177], v[46:49]
	v_mfma_f32_16x16x32_bf16 v[42:45], v[166:169], v[174:177], v[42:45]
	v_mfma_f32_16x16x32_bf16 v[38:41], v[152:155], v[182:185], v[38:41]
	v_mfma_f32_16x16x32_bf16 v[34:37], v[166:169], v[182:185], v[34:37]
	v_mfma_f32_16x16x32_bf16 v[18:21], v[152:155], v[190:193], v[18:21]
	v_mfma_f32_16x16x32_bf16 v[14:17], v[166:169], v[190:193], v[14:17]
	v_mfma_f32_16x16x32_bf16 v[6:9], v[152:155], v[198:201], v[6:9]
	v_mfma_f32_16x16x32_bf16 v[2:5], v[166:169], v[198:201], v[2:5]
	v_mfma_f32_16x16x32_bf16 v[46:49], v[156:159], v[178:181], v[46:49]
	v_mfma_f32_16x16x32_bf16 v[42:45], v[170:173], v[178:181], v[42:45]
	v_mfma_f32_16x16x32_bf16 v[38:41], v[156:159], v[186:189], v[38:41]
	v_mfma_f32_16x16x32_bf16 v[34:37], v[170:173], v[186:189], v[34:37]
	v_mfma_f32_16x16x32_bf16 v[18:21], v[156:159], v[194:197], v[18:21]
	v_mfma_f32_16x16x32_bf16 v[14:17], v[170:173], v[194:197], v[14:17]
	v_mfma_f32_16x16x32_bf16 v[6:9], v[156:159], v[202:205], v[6:9]
	v_mfma_f32_16x16x32_bf16 v[2:5], v[170:173], v[202:205], v[2:5]
	s_setprio 0
	s_barrier
	s_add_i32 s29, s29, 2
	s_add_u32 s27, s27, 0x100
	s_addc_u32 s28, s28, 0
	s_cmpk_gt_u32 s29, 0x53
	s_mov_b64 s[54:55], s[4:5]
	s_cbranch_scc0 .LBB0_1476
	s_and_b64 vcc, exec, s[46:47]
	s_cbranch_vccz .LBB0_1479
	s_barrier

; #define PG8_STAGE(bufoff, gbase, voff) do { _Pragma("unroll") for (int _i = 0; _i < 2; ++_i) \
;         __builtin_amdgcn_global_load_lds((const unsigned*)((const char*)(gbase) + (voff)[_i]), (LAS unsigned*)(lds + (bufoff) + ldsw + _i * 8192), 16, 0, 0); } while (0)
; #define PG8_LDA(dst, b, h) do { _Pragma("unroll") for (int m = 0; m < 4; ++m) _Pragma("unroll") for (int k = 0; k < 2; ++k) dst[m][k] = *(const LAS bf16x8*)(lds + PG8_SA(b, h) + aoff + m * 2048 + k * 1024); } while (0)
; #define PG8_LDB(dst, b, h) do { _Pragma("unroll") for (int n = 0; n < 2; ++n) _Pragma("unroll") for (int k = 0; k < 2; ++k) dst[n][k] = *(const LAS bf16x8*)(lds + PG8_SB(b, h) + boff + n * 2048 + k * 1024); } while (0)
; #define PG8_WAIT_V(n) asm volatile("s_waitcnt vmcnt(" #n ")" ::: "memory")
; template <class Epi, int AMODE>
; __device__ __forceinline__ void gemm_phase(LAS unsigned char* lds, const Gemm g, const StaticOrder& S, const Epi& E, int stagger_us, int tid_in) {
;     ...
;         for (int t = 0; t < nt; t += 2) {
;             const bool last = (t == nt - 2);
;             const char* a1 = cA + (size_t)(t + 1) * kstep;
;             const char* a2 = last ? nA : cA + (size_t)(t + 2) * kstep; const char* b2 = last ? nB : cB + (size_t)(t + 2) * kstep;
;             const char* a3 = a2 + kstep; const char* b3 = b2 + kstep;
;             PG8_LDB(B0, 0, 0); PG8_LDB(B1, 0, 1); PG8_SCHED; PG8_LDA(At, 0, 0); PG8_STAGE(PG8_SA(1, 1), a1 + hstepA, voffA);
;             PG8_WAIT_V(8); PG8_WAIT_L(0); PG8_BAR; PG8_MMA(0, 0, At, B0); PG8_MMA(0, 1, At, B1); PG8_BAR; PG8_SCHED;
;             PG8_LDA(At, 0, 1); PG8_STAGE(PG8_SB(0, 0), b2, voffB); PG8_STAGE(PG8_SB(0, 1), b2 + hstepB, voffB); PG8_STAGE(PG8_SA(0, 0), a2, voffA);
;             PG8_WAIT_V(8); PG8_WAIT_L(0); PG8_BAR; PG8_MMA(1, 0, At, B0); PG8_MMA(1, 1, At, B1); PG8_BAR; PG8_SCHED;
;             PG8_LDB(B0, 1, 0); PG8_LDB(B1, 1, 1); PG8_SCHED; PG8_LDA(At, 1, 0); PG8_STAGE(PG8_SA(0, 1), a2 + hstepA, voffA);
;             PG8_WAIT_V(8); PG8_WAIT_L(0); PG8_BAR; PG8_MMA(0, 0, At, B0); PG8_MMA(0, 1, At, B1); PG8_BAR; PG8_SCHED;
;             PG8_LDA(At, 1, 1); PG8_STAGE(PG8_SB(1, 0), b3, voffB); PG8_STAGE(PG8_SB(1, 1), b3 + hstepB, voffB); PG8_STAGE(PG8_SA(1, 0), a3, voffA);
;             PG8_WAIT_V(8); PG8_WAIT_L(0); PG8_BAR; PG8_MMA(1, 0, At, B0); PG8_MMA(1, 1, At, B1); PG8_BAR; PG8_SCHED;
.LBB0_1498:
	s_add_u32 s4, s46, 0x100
	s_addc_u32 s5, s47, 0
	s_add_i32 s30, 0, 0x10000
	s_cmpk_eq_i32 s29, 0x52
	s_cselect_b32 s59, s41, s5
	s_cselect_b32 s58, s40, s4
	s_cselect_b32 s7, s57, s28
	s_cselect_b32 s6, s56, s27
	s_add_i32 s34, 0, 0x14000
	v_add_u32_e32 v62, s30, v209
	v_add_u32_e32 v158, s34, v209
	ds_read_b128 v[50:53], v62
	ds_read_b128 v[54:57], v62 offset:1024
	ds_read_b128 v[58:61], v62 offset:2048
	ds_read_b128 v[62:65], v62 offset:3072
	ds_read_b128 v[146:149], v158
	ds_read_b128 v[150:153], v158 offset:1024
	ds_read_b128 v[154:157], v158 offset:2048
	ds_read_b128 v[158:161], v158 offset:3072
	v_lshl_add_u64 v[200:201], s[46:47], 0, v[176:177]
	s_add_i32 m0, s13, 0xc000
	ds_read_b128 v[162:165], v215
	ds_read_b128 v[166:169], v215 offset:1024
	ds_read_b128 v[170:173], v215 offset:2048
	ds_read_b128 v[180:183], v215 offset:3072
	ds_read_b128 v[184:187], v215 offset:4096
	ds_read_b128 v[188:191], v215 offset:5120
	ds_read_b128 v[192:195], v215 offset:6144
	ds_read_b128 v[196:199], v215 offset:7168
	global_load_lds_dwordx4 v[200:201], off
	s_add_i32 m0, s13, 0xe000
	v_lshl_add_u64 v[200:201], s[46:47], 0, v[178:179]
	global_load_lds_dwordx4 v[200:201], off
	s_setprio 1
	s_waitcnt vmcnt(8) lgkmcnt(0)
	v_mfma_f32_16x16x32_bf16 v[142:145], v[50:53], v[162:165], v[142:145]
	v_mfma_f32_16x16x32_bf16 v[138:141], v[58:61], v[162:165], v[138:141]
	s_barrier
	v_mfma_f32_16x16x32_bf16 v[126:129], v[50:53], v[170:173], v[126:129]
	v_mfma_f32_16x16x32_bf16 v[122:125], v[58:61], v[170:173], v[122:125]
	v_mfma_f32_16x16x32_bf16 v[110:113], v[50:53], v[184:187], v[110:113]
	v_mfma_f32_16x16x32_bf16 v[106:109], v[58:61], v[184:187], v[106:109]
	v_mfma_f32_16x16x32_bf16 v[94:97], v[50:53], v[192:195], v[94:97]
	v_mfma_f32_16x16x32_bf16 v[90:93], v[58:61], v[192:195], v[90:93]
	v_mfma_f32_16x16x32_bf16 v[142:145], v[54:57], v[166:169], v[142:145]
	v_mfma_f32_16x16x32_bf16 v[138:141], v[62:65], v[166:169], v[138:141]
	v_mfma_f32_16x16x32_bf16 v[126:129], v[54:57], v[180:183], v[126:129]
	v_mfma_f32_16x16x32_bf16 v[122:125], v[62:65], v[180:183], v[122:125]
	v_mfma_f32_16x16x32_bf16 v[110:113], v[54:57], v[188:191], v[110:113]
	v_mfma_f32_16x16x32_bf16 v[106:109], v[62:65], v[188:191], v[106:109]
	v_mfma_f32_16x16x32_bf16 v[94:97], v[54:57], v[196:199], v[94:97]
	v_mfma_f32_16x16x32_bf16 v[90:93], v[62:65], v[196:199], v[90:93]
	v_mfma_f32_16x16x32_bf16 v[134:137], v[146:149], v[162:165], v[134:137]
	v_mfma_f32_16x16x32_bf16 v[130:133], v[154:157], v[162:165], v[130:133]
	v_mfma_f32_16x16x32_bf16 v[118:121], v[146:149], v[170:173], v[118:121]
	v_mfma_f32_16x16x32_bf16 v[114:117], v[154:157], v[170:173], v[114:117]
	v_mfma_f32_16x16x32_bf16 v[102:105], v[146:149], v[184:187], v[102:105]
	v_mfma_f32_16x16x32_bf16 v[98:101], v[154:157], v[184:187], v[98:101]
	v_mfma_f32_16x16x32_bf16 v[86:89], v[146:149], v[192:195], v[86:89]
	v_mfma_f32_16x16x32_bf16 v[82:85], v[154:157], v[192:195], v[82:85]
	v_mfma_f32_16x16x32_bf16 v[134:137], v[150:153], v[166:169], v[134:137]
	v_mfma_f32_16x16x32_bf16 v[130:133], v[158:161], v[166:169], v[130:133]
	v_mfma_f32_16x16x32_bf16 v[118:121], v[150:153], v[180:183], v[118:121]
	v_mfma_f32_16x16x32_bf16 v[114:117], v[158:161], v[180:183], v[114:117]
	v_mfma_f32_16x16x32_bf16 v[102:105], v[150:153], v[188:191], v[102:105]
	v_mfma_f32_16x16x32_bf16 v[98:101], v[158:161], v[188:191], v[98:101]
	v_mfma_f32_16x16x32_bf16 v[86:89], v[150:153], v[196:199], v[86:89]
	v_mfma_f32_16x16x32_bf16 v[82:85], v[158:161], v[196:199], v[82:85]
	s_setprio 0
	s_barrier
	s_add_i32 s30, s30, s12
	v_lshl_add_u64 v[200:201], s[6:7], 0, v[0:1]
	s_mov_b32 m0, s30
	ds_read_b128 v[162:165], v215 offset:16384
	ds_read_b128 v[166:169], v215 offset:17408
	ds_read_b128 v[170:173], v215 offset:18432
	ds_read_b128 v[180:183], v215 offset:19456
	ds_read_b128 v[184:187], v215 offset:20480
	ds_read_b128 v[188:191], v215 offset:21504
	ds_read_b128 v[192:195], v215 offset:22528
	ds_read_b128 v[196:199], v215 offset:23552
	global_load_lds_dwordx4 v[200:201], off
	s_add_i32 m0, s30, 0x2000
	s_add_u32 s30, s6, 0x158000
	v_lshl_add_u64 v[202:203], s[6:7], 0, v[174:175]
	s_addc_u32 s31, s7, 0
	s_add_i32 s34, s34, s12
	global_load_lds_dwordx4 v[202:203], off
	v_lshl_add_u64 v[204:205], s[30:31], 0, v[0:1]
	s_mov_b32 m0, s34
	v_lshl_add_u64 v[206:207], s[58:59], 0, v[174:175]
	global_load_lds_dwordx4 v[204:205], off
	s_add_i32 m0, s34, 0x2000
	v_lshl_add_u64 v[204:205], s[30:31], 0, v[174:175]
	global_load_lds_dwordx4 v[204:205], off
	s_mov_b32 m0, s13
	v_lshl_add_u64 v[204:205], s[58:59], 0, v[0:1]
	global_load_lds_dwordx4 v[204:205], off
	s_mov_b32 m0, s24
	s_nop 0
	global_load_lds_dwordx4 v[206:207], off
	s_setprio 1
	s_waitcnt vmcnt(8) lgkmcnt(0)
	v_mfma_f32_16x16x32_bf16 v[78:81], v[50:53], v[162:165], v[78:81]
	v_mfma_f32_16x16x32_bf16 v[74:77], v[58:61], v[162:165], v[74:77]
	s_barrier
; #define PG8_STAGE(bufoff, gbase, voff) do { _Pragma("unroll") for (int _i = 0; _i < 2; ++_i) \
;         __builtin_amdgcn_global_load_lds((const unsigned*)((const char*)(gbase) + (voff)[_i]), (LAS unsigned*)(lds + (bufoff) + ldsw + _i * 8192), 16, 0, 0); } while (0)
; #define PG8_LDA(dst, b, h) do { _Pragma("unroll") for (int m = 0; m < 4; ++m) _Pragma("unroll") for (int k = 0; k < 2; ++k) dst[m][k] = *(const LAS bf16x8*)(lds + PG8_SA(b, h) + aoff + m * 2048 + k * 1024); } while (0)
; #define PG8_LDB(dst, b, h) do { _Pragma("unroll") for (int n = 0; n < 2; ++n) _Pragma("unroll") for (int k = 0; k < 2; ++k) dst[n][k] = *(const LAS bf16x8*)(lds + PG8_SB(b, h) + boff + n * 2048 + k * 1024); } while (0)
; #define PG8_WAIT_V(n) asm volatile("s_waitcnt vmcnt(" #n ")" ::: "memory")
; template <class Epi, int AMODE>
; __device__ __forceinline__ void gemm_phase(LAS unsigned char* lds, const Gemm g, const StaticOrder& S, const Epi& E, int stagger_us, int tid_in) {
;     ...
;         for (int t = 0; t < nt; t += 2) {
;             const bool last = (t == nt - 2);
;             const char* a1 = cA + (size_t)(t + 1) * kstep;
;             const char* a2 = last ? nA : cA + (size_t)(t + 2) * kstep; const char* b2 = last ? nB : cB + (size_t)(t + 2) * kstep;
;             const char* a3 = a2 + kstep; const char* b3 = b2 + kstep;
;             PG8_LDB(B0, 0, 0); PG8_LDB(B1, 0, 1); PG8_SCHED; PG8_LDA(At, 0, 0); PG8_STAGE(PG8_SA(1, 1), a1 + hstepA, voffA);
;             PG8_WAIT_V(8); PG8_WAIT_L(0); PG8_BAR; PG8_MMA(0, 0, At, B0); PG8_MMA(0, 1, At, B1); PG8_BAR; PG8_SCHED;
;             PG8_LDA(At, 0, 1); PG8_STAGE(PG8_SB(0, 0), b2, voffB); PG8_STAGE(PG8_SB(0, 1), b2 + hstepB, voffB); PG8_STAGE(PG8_SA(0, 0), a2, voffA);
;             PG8_WAIT_V(8); PG8_WAIT_L(0); PG8_BAR; PG8_MMA(1, 0, At, B0); PG8_MMA(1, 1, At, B1); PG8_BAR; PG8_SCHED;
;             PG8_LDB(B0, 1, 0); PG8_LDB(B1, 1, 1); PG8_SCHED; PG8_LDA(At, 1, 0); PG8_STAGE(PG8_SA(0, 1), a2 + hstepA, voffA);
;             PG8_WAIT_V(8); PG8_WAIT_L(0); PG8_BAR; PG8_MMA(0, 0, At, B0); PG8_MMA(0, 1, At, B1); PG8_BAR; PG8_SCHED;
;             PG8_LDA(At, 1, 1); PG8_STAGE(PG8_SB(1, 0), b3, voffB); PG8_STAGE(PG8_SB(1, 1), b3 + hstepB, voffB); PG8_STAGE(PG8_SA(1, 0), a3, voffA);
;             PG8_WAIT_V(8); PG8_WAIT_L(0); PG8_BAR; PG8_MMA(1, 0, At, B0); PG8_MMA(1, 1, At, B1); PG8_BAR; PG8_SCHED;
	v_mfma_f32_16x16x32_bf16 v[46:49], v[50:53], v[170:173], v[46:49]
	v_mfma_f32_16x16x32_bf16 v[42:45], v[58:61], v[170:173], v[42:45]
	v_mfma_f32_16x16x32_bf16 v[30:33], v[50:53], v[184:187], v[30:33]
	v_mfma_f32_16x16x32_bf16 v[26:29], v[58:61], v[184:187], v[26:29]
	v_mfma_f32_16x16x32_bf16 v[14:17], v[50:53], v[192:195], v[14:17]
	v_mfma_f32_16x16x32_bf16 v[10:13], v[58:61], v[192:195], v[10:13]
	v_mfma_f32_16x16x32_bf16 v[78:81], v[54:57], v[166:169], v[78:81]
	v_mfma_f32_16x16x32_bf16 v[74:77], v[62:65], v[166:169], v[74:77]
	v_mfma_f32_16x16x32_bf16 v[46:49], v[54:57], v[180:183], v[46:49]
	v_mfma_f32_16x16x32_bf16 v[42:45], v[62:65], v[180:183], v[42:45]
	v_mfma_f32_16x16x32_bf16 v[30:33], v[54:57], v[188:191], v[30:33]
	v_mfma_f32_16x16x32_bf16 v[26:29], v[62:65], v[188:191], v[26:29]
	v_mfma_f32_16x16x32_bf16 v[14:17], v[54:57], v[196:199], v[14:17]
	v_mfma_f32_16x16x32_bf16 v[10:13], v[62:65], v[196:199], v[10:13]
	v_mfma_f32_16x16x32_bf16 v[38:41], v[146:149], v[170:173], v[38:41]
	v_mfma_f32_16x16x32_bf16 v[34:37], v[154:157], v[170:173], v[34:37]
	v_mfma_f32_16x16x32_bf16 v[22:25], v[146:149], v[184:187], v[22:25]
	v_mfma_f32_16x16x32_bf16 v[18:21], v[154:157], v[184:187], v[18:21]
	v_mfma_f32_16x16x32_bf16 v[6:9], v[146:149], v[192:195], v[6:9]
	v_mfma_f32_16x16x32_bf16 v[2:5], v[154:157], v[192:195], v[2:5]
	v_mfma_f32_16x16x32_bf16 v[50:53], v[146:149], v[162:165], v[70:73]
	v_mfma_f32_16x16x32_bf16 v[54:57], v[154:157], v[162:165], v[66:69]
	v_mfma_f32_16x16x32_bf16 v[38:41], v[150:153], v[180:183], v[38:41]
	v_mfma_f32_16x16x32_bf16 v[34:37], v[158:161], v[180:183], v[34:37]
	v_mfma_f32_16x16x32_bf16 v[22:25], v[150:153], v[188:191], v[22:25]
	v_mfma_f32_16x16x32_bf16 v[18:21], v[158:161], v[188:191], v[18:21]
	v_mfma_f32_16x16x32_bf16 v[6:9], v[150:153], v[196:199], v[6:9]
	v_mfma_f32_16x16x32_bf16 v[2:5], v[158:161], v[196:199], v[2:5]
	v_mfma_f32_16x16x32_bf16 v[50:53], v[150:153], v[166:169], v[50:53]
	v_mfma_f32_16x16x32_bf16 v[54:57], v[158:161], v[166:169], v[54:57]
	s_setprio 0
	s_barrier
	s_add_i32 s34, 0, 0x18000
	s_add_i32 s35, 0, 0x1c000
	v_add_u32_e32 v70, s34, v209
	v_add_u32_e32 v158, s35, v209
	ds_read_b128 v[58:61], v70
	ds_read_b128 v[62:65], v70 offset:1024
	ds_read_b128 v[66:69], v70 offset:2048
	ds_read_b128 v[70:73], v70 offset:3072
	ds_read_b128 v[146:149], v158
	ds_read_b128 v[150:153], v158 offset:1024
	ds_read_b128 v[154:157], v158 offset:2048
	ds_read_b128 v[158:161], v158 offset:3072
	s_add_u32 s30, s58, 0x158000
	s_addc_u32 s31, s59, 0
	s_mov_b32 m0, s25
	v_lshl_add_u64 v[210:211], s[30:31], 0, v[0:1]
	ds_read_b128 v[162:165], v215 offset:32768
	ds_read_b128 v[166:169], v215 offset:33792
	ds_read_b128 v[170:173], v215 offset:34816
	ds_read_b128 v[180:183], v215 offset:35840
	ds_read_b128 v[184:187], v215 offset:36864
	ds_read_b128 v[188:191], v215 offset:37888
	ds_read_b128 v[192:195], v215 offset:38912
	ds_read_b128 v[196:199], v215 offset:39936
	global_load_lds_dwordx4 v[210:211], off
	s_mov_b32 m0, s66
	v_lshl_add_u64 v[210:211], s[30:31], 0, v[174:175]
	global_load_lds_dwordx4 v[210:211], off
	s_setprio 1
	s_waitcnt vmcnt(8) lgkmcnt(0)
	v_mfma_f32_16x16x32_bf16 v[142:145], v[58:61], v[162:165], v[142:145]
	v_mfma_f32_16x16x32_bf16 v[138:141], v[66:69], v[162:165], v[138:141]
	s_barrier
	v_mfma_f32_16x16x32_bf16 v[126:129], v[58:61], v[170:173], v[126:129]
	v_mfma_f32_16x16x32_bf16 v[122:125], v[66:69], v[170:173], v[122:125]
	v_mfma_f32_16x16x32_bf16 v[110:113], v[58:61], v[184:187], v[110:113]
	v_mfma_f32_16x16x32_bf16 v[106:109], v[66:69], v[184:187], v[106:109]
	v_mfma_f32_16x16x32_bf16 v[94:97], v[58:61], v[192:195], v[94:97]
	v_mfma_f32_16x16x32_bf16 v[90:93], v[66:69], v[192:195], v[90:93]
	v_mfma_f32_16x16x32_bf16 v[142:145], v[62:65], v[166:169], v[142:145]
	v_mfma_f32_16x16x32_bf16 v[138:141], v[70:73], v[166:169], v[138:141]
	v_mfma_f32_16x16x32_bf16 v[126:129], v[62:65], v[180:183], v[126:129]
	v_mfma_f32_16x16x32_bf16 v[122:125], v[70:73], v[180:183], v[122:125]
	v_mfma_f32_16x16x32_bf16 v[110:113], v[62:65], v[188:191], v[110:113]
	v_mfma_f32_16x16x32_bf16 v[106:109], v[70:73], v[188:191], v[106:109]
	v_mfma_f32_16x16x32_bf16 v[94:97], v[62:65], v[196:199], v[94:97]
	v_mfma_f32_16x16x32_bf16 v[90:93], v[70:73], v[196:199], v[90:93]
	v_mfma_f32_16x16x32_bf16 v[134:137], v[146:149], v[162:165], v[134:137]
	v_mfma_f32_16x16x32_bf16 v[130:133], v[154:157], v[162:165], v[130:133]
	v_mfma_f32_16x16x32_bf16 v[118:121], v[146:149], v[170:173], v[118:121]
	v_mfma_f32_16x16x32_bf16 v[114:117], v[154:157], v[170:173], v[114:117]
	v_mfma_f32_16x16x32_bf16 v[102:105], v[146:149], v[184:187], v[102:105]
	v_mfma_f32_16x16x32_bf16 v[98:101], v[154:157], v[184:187], v[98:101]
	v_mfma_f32_16x16x32_bf16 v[86:89], v[146:149], v[192:195], v[86:89]
	v_mfma_f32_16x16x32_bf16 v[82:85], v[154:157], v[192:195], v[82:85]
	v_mfma_f32_16x16x32_bf16 v[134:137], v[150:153], v[166:169], v[134:137]
	v_mfma_f32_16x16x32_bf16 v[130:133], v[158:161], v[166:169], v[130:133]
	v_mfma_f32_16x16x32_bf16 v[118:121], v[150:153], v[180:183], v[118:121]
	v_mfma_f32_16x16x32_bf16 v[114:117], v[158:161], v[180:183], v[114:117]
	v_mfma_f32_16x16x32_bf16 v[102:105], v[150:153], v[188:191], v[102:105]
	v_mfma_f32_16x16x32_bf16 v[98:101], v[158:161], v[188:191], v[98:101]
	v_mfma_f32_16x16x32_bf16 v[86:89], v[150:153], v[196:199], v[86:89]
	v_mfma_f32_16x16x32_bf16 v[82:85], v[158:161], v[196:199], v[82:85]
	s_setprio 0
	s_barrier
; #define PG8_STAGE(bufoff, gbase, voff) do { _Pragma("unroll") for (int _i = 0; _i < 2; ++_i) \
;         __builtin_amdgcn_global_load_lds((const unsigned*)((const char*)(gbase) + (voff)[_i]), (LAS unsigned*)(lds + (bufoff) + ldsw + _i * 8192), 16, 0, 0); } while (0)
; #define PG8_LDA(dst, b, h) do { _Pragma("unroll") for (int m = 0; m < 4; ++m) _Pragma("unroll") for (int k = 0; k < 2; ++k) dst[m][k] = *(const LAS bf16x8*)(lds + PG8_SA(b, h) + aoff + m * 2048 + k * 1024); } while (0)
; #define PG8_LDB(dst, b, h) do { _Pragma("unroll") for (int n = 0; n < 2; ++n) _Pragma("unroll") for (int k = 0; k < 2; ++k) dst[n][k] = *(const LAS bf16x8*)(lds + PG8_SB(b, h) + boff + n * 2048 + k * 1024); } while (0)
; #define PG8_BAR __builtin_amdgcn_s_barrier()
; template <class Epi, int AMODE>
; __device__ __forceinline__ void gemm_phase(LAS unsigned char* lds, const Gemm g, const StaticOrder& S, const Epi& E, int stagger_us, int tid_in) {
;     ...
;         for (int t = 0; t < nt; t += 2) {
;             const bool last = (t == nt - 2);
;             const char* a1 = cA + (size_t)(t + 1) * kstep;
;             const char* a2 = last ? nA : cA + (size_t)(t + 2) * kstep; const char* b2 = last ? nB : cB + (size_t)(t + 2) * kstep;
;             const char* a3 = a2 + kstep; const char* b3 = b2 + kstep;
;             PG8_LDB(B0, 0, 0); PG8_LDB(B1, 0, 1); PG8_SCHED; PG8_LDA(At, 0, 0); PG8_STAGE(PG8_SA(1, 1), a1 + hstepA, voffA);
;             PG8_WAIT_V(8); PG8_WAIT_L(0); PG8_BAR; PG8_MMA(0, 0, At, B0); PG8_MMA(0, 1, At, B1); PG8_BAR; PG8_SCHED;
;             PG8_LDA(At, 0, 1); PG8_STAGE(PG8_SB(0, 0), b2, voffB); PG8_STAGE(PG8_SB(0, 1), b2 + hstepB, voffB); PG8_STAGE(PG8_SA(0, 0), a2, voffA);
;             PG8_WAIT_V(8); PG8_WAIT_L(0); PG8_BAR; PG8_MMA(1, 0, At, B0); PG8_MMA(1, 1, At, B1); PG8_BAR; PG8_SCHED;
;             PG8_LDB(B0, 1, 0); PG8_LDB(B1, 1, 1); PG8_SCHED; PG8_LDA(At, 1, 0); PG8_STAGE(PG8_SA(0, 1), a2 + hstepA, voffA);
;             PG8_WAIT_V(8); PG8_WAIT_L(0); PG8_BAR; PG8_MMA(0, 0, At, B0); PG8_MMA(0, 1, At, B1); PG8_BAR; PG8_SCHED;
;             PG8_LDA(At, 1, 1); PG8_STAGE(PG8_SB(1, 0), b3, voffB); PG8_STAGE(PG8_SB(1, 1), b3 + hstepB, voffB); PG8_STAGE(PG8_SA(1, 0), a3, voffA);
;             PG8_WAIT_V(8); PG8_WAIT_L(0); PG8_BAR; PG8_MMA(1, 0, At, B0); PG8_MMA(1, 1, At, B1); PG8_BAR; PG8_SCHED;
;         }
;         if (wr == 0) PG8_BAR;
	s_add_i32 s30, s34, s12
	v_lshl_add_u64 v[200:201], v[200:201], 0, s[74:75]
	s_mov_b32 m0, s30
	ds_read_b128 v[162:165], v215 offset:49152
	ds_read_b128 v[166:169], v215 offset:50176
	ds_read_b128 v[170:173], v215 offset:51200
	ds_read_b128 v[180:183], v215 offset:52224
	ds_read_b128 v[184:187], v215 offset:53248
	ds_read_b128 v[188:191], v215 offset:54272
	ds_read_b128 v[192:195], v215 offset:55296
	ds_read_b128 v[196:199], v215 offset:56320
	global_load_lds_dwordx4 v[200:201], off
	s_add_i32 m0, s30, 0x2000
	s_add_u32 s6, s6, 0x158080
	v_lshl_add_u64 v[200:201], v[202:203], 0, s[74:75]
	s_addc_u32 s7, s7, 0
	s_add_i32 s30, s35, s12
	global_load_lds_dwordx4 v[200:201], off
	s_mov_b32 m0, s30
	v_lshl_add_u64 v[200:201], s[6:7], 0, v[0:1]
	global_load_lds_dwordx4 v[200:201], off
	s_add_i32 m0, s30, 0x2000
	v_lshl_add_u64 v[200:201], s[6:7], 0, v[174:175]
	global_load_lds_dwordx4 v[200:201], off
	s_mov_b32 m0, s79
	v_lshl_add_u64 v[200:201], v[204:205], 0, s[74:75]
	global_load_lds_dwordx4 v[200:201], off
	s_mov_b32 m0, s83
	v_lshl_add_u64 v[200:201], v[206:207], 0, s[74:75]
	global_load_lds_dwordx4 v[200:201], off
	s_setprio 1
	s_waitcnt vmcnt(8) lgkmcnt(0)
	v_mfma_f32_16x16x32_bf16 v[78:81], v[58:61], v[162:165], v[78:81]
	v_mfma_f32_16x16x32_bf16 v[74:77], v[66:69], v[162:165], v[74:77]
	s_barrier
	v_mfma_f32_16x16x32_bf16 v[46:49], v[58:61], v[170:173], v[46:49]
	v_mfma_f32_16x16x32_bf16 v[42:45], v[66:69], v[170:173], v[42:45]
	v_mfma_f32_16x16x32_bf16 v[30:33], v[58:61], v[184:187], v[30:33]
	v_mfma_f32_16x16x32_bf16 v[26:29], v[66:69], v[184:187], v[26:29]
	v_mfma_f32_16x16x32_bf16 v[14:17], v[58:61], v[192:195], v[14:17]
	v_mfma_f32_16x16x32_bf16 v[10:13], v[66:69], v[192:195], v[10:13]
	v_mfma_f32_16x16x32_bf16 v[78:81], v[62:65], v[166:169], v[78:81]
	v_mfma_f32_16x16x32_bf16 v[74:77], v[70:73], v[166:169], v[74:77]
	v_mfma_f32_16x16x32_bf16 v[46:49], v[62:65], v[180:183], v[46:49]
	v_mfma_f32_16x16x32_bf16 v[42:45], v[70:73], v[180:183], v[42:45]
	v_mfma_f32_16x16x32_bf16 v[30:33], v[62:65], v[188:191], v[30:33]
	v_mfma_f32_16x16x32_bf16 v[26:29], v[70:73], v[188:191], v[26:29]
	v_mfma_f32_16x16x32_bf16 v[14:17], v[62:65], v[196:199], v[14:17]
	v_mfma_f32_16x16x32_bf16 v[10:13], v[70:73], v[196:199], v[10:13]
	v_mfma_f32_16x16x32_bf16 v[50:53], v[146:149], v[162:165], v[50:53]
	v_mfma_f32_16x16x32_bf16 v[70:73], v[150:153], v[166:169], v[50:53]
	v_mfma_f32_16x16x32_bf16 v[50:53], v[154:157], v[162:165], v[54:57]
	v_mfma_f32_16x16x32_bf16 v[38:41], v[146:149], v[170:173], v[38:41]
	v_mfma_f32_16x16x32_bf16 v[34:37], v[154:157], v[170:173], v[34:37]
	v_mfma_f32_16x16x32_bf16 v[22:25], v[146:149], v[184:187], v[22:25]
	v_mfma_f32_16x16x32_bf16 v[18:21], v[154:157], v[184:187], v[18:21]
	v_mfma_f32_16x16x32_bf16 v[6:9], v[146:149], v[192:195], v[6:9]
	v_mfma_f32_16x16x32_bf16 v[2:5], v[154:157], v[192:195], v[2:5]
	v_mfma_f32_16x16x32_bf16 v[66:69], v[158:161], v[166:169], v[50:53]
	v_mfma_f32_16x16x32_bf16 v[38:41], v[150:153], v[180:183], v[38:41]
	v_mfma_f32_16x16x32_bf16 v[34:37], v[158:161], v[180:183], v[34:37]
	v_mfma_f32_16x16x32_bf16 v[22:25], v[150:153], v[188:191], v[22:25]
	v_mfma_f32_16x16x32_bf16 v[18:21], v[158:161], v[188:191], v[18:21]
	v_mfma_f32_16x16x32_bf16 v[6:9], v[150:153], v[196:199], v[6:9]
	v_mfma_f32_16x16x32_bf16 v[2:5], v[158:161], v[196:199], v[2:5]
	s_setprio 0
	s_barrier
	s_add_i32 s29, s29, 2
	s_add_u32 s27, s27, 0x100
	s_addc_u32 s28, s28, 0
	s_cmpk_gt_u32 s29, 0x53
	s_mov_b64 s[46:47], s[4:5]
	s_cbranch_scc0 .LBB0_1498
	s_and_b64 vcc, exec, s[54:55]
	s_cbranch_vccz .LBB0_1501
	s_barrier
